# MERGE hook: 16 gate loads in flight, g_a loads nt; MERGE epilogue: all 16 g_b loads up front; pool LDS half-swap
# baseline (speedup 1.0000x reference)
; __device__ __forceinline__ void mix_phase(LAS unsigned char* lds, const Params& p, const int layer) {
;     ...
;             if (prt) {
;                 const int t0 = r0 & 2047;
; #pragma unroll
;                 for (int k = 0; k < 3; ++k) { const int i = i0 + 16 * k; const float f = ((i < 47) && (t0 - 15 + i >= 0)) ? 1.0f : 0.0f; BF8_TO_F32(vw[k], a0, a1);
;                     if (i < 47) { *(LAS f32x4*)(SL + i * 264 + q * 8) = a0 * f; *(LAS f32x4*)(SL + i * 264 + q * 8 + 4) = a1 * f; } }
;             } else {
;                 const float* spool = p.in[2] + (size_t)layer * 128 * 15 * PW; const int bs0 = (r0 - NP) >> 3;
; #pragma unroll 2
;                 for (int i = tid >> 5; i < 92; i += 16) { const int sq = i / 23, ii = i - sq * 23; f32x4 a0, a1;
;                     if (ii < 15) { const float* sp = spool + ((size_t)(bs0 + sq) * 15 + ii) * PW + col; a0 = *(const f32x4*)sp; a1 = *(const f32x4*)(sp + 4); }
;                     else { const v4u vv = *(const v4u*)(PROJ + (size_t)(NP + (bs0 + sq) * 8 + (ii - 15)) * NC + C_UA + col); BF8_TO_F32(vv, c0_, c1_); a0 = c0_; a1 = c1_; }
;                     *(LAS f32x4*)(SL + i * 264 + q * 8) = a0; *(LAS f32x4*)(SL + i * 264 + q * 8 + 4) = a1; }
;             }
;             __syncthreads();
;             v2u sgc[2][2];
; #pragma unroll
;             for (int m = 0; m < 2; ++m)
; #pragma unroll
;                 for (int n = 0; n < 2; ++n) sgc[m][n] = sgv[m][n];
;             if (ua + G < NUA) MIX_PREFETCH_A(ua + G);
; #pragma unroll
;             for (int i = 0; i < 2; ++i) {
;                 const int rl = (tid >> 5) + 16 * i, bi = prt ? rl + 15 : (rl >> 3) * 23 + 15 + (rl & 7), t = (r0 + rl) & 2047;
;                 const LAS float* sp = SL + bi * 264 + q * 8;
;                 const f32x4 u0 = *(const LAS f32x4*)sp, u1 = *(const LAS f32x4*)(sp + 4);
;                 f32x4 s0 = u0, s1 = u1;
; #pragma unroll 4
;                 for (int j = 1; j < w; ++j) { s0 += *(const LAS f32x4*)(sp - j * 264); s1 += *(const LAS f32x4*)(sp - j * 264 + 4); }
;                 const int cnt = (prt && t + 1 < w) ? t + 1 : w; const float inv = 1.0f / (float)cnt;
;                 const f32x4 d0 = s0 * inv - u0, d1 = s1 * inv - u1;
;                 v4u o; o.x = pk2(d0[0], d0[1]); o.y = pk2(d0[2], d0[3]); o.z = pk2(d1[0], d1[1]); o.w = pk2(d1[2], d1[3]);
;                 *(LAS v4u*)(At + rl * 264 + q * 8) = o;
.LBB0_550:
	s_lshl_b32 s0, s56, 10
	s_mul_i32 s2, s56, 0x1e0000
	v_readlane_b32 s56, v251, 37
	v_or_b32_e32 v16, s46, v135
	s_mov_b32 s1, s80
	v_readlane_b32 s57, v251, 38
	v_ashrrev_i32_e32 v17, 31, v16
	v_readlane_b32 s12, v248, 35
	s_lshl_b64 s[0:1], s[0:1], 2
	v_readlane_b32 s58, v251, 39
	v_readlane_b32 s59, v251, 40
	v_readlane_b32 s60, v251, 41
	v_readlane_b32 s61, v251, 42
	v_readlane_b32 s62, v251, 43
	v_readlane_b32 s63, v251, 44
	v_readlane_b32 s64, v251, 45
	v_readlane_b32 s65, v251, 46
	v_readlane_b32 s66, v251, 47
	v_readlane_b32 s67, v251, 48
	v_readlane_b32 s68, v251, 49
	v_readlane_b32 s69, v251, 50
	v_readlane_b32 s70, v251, 51
	v_readlane_b32 s71, v251, 52
	s_mov_b64 s[36:37], s[56:57]
	v_lshlrev_b64 v[16:17], 9, v[16:17]
	v_readlane_b32 s13, v248, 36
	s_mov_b32 s3, s80
	s_add_u32 s5, s36, s0
	v_readlane_b32 s56, v251, 21
	v_lshl_add_u64 v[16:17], s[12:13], 0, v[16:17]
	v_lshlrev_b32_e32 v0, 4, v137
	s_addc_u32 s6, s37, s1
	s_lshl_b64 s[0:1], s[2:3], 2
	v_readlane_b32 s60, v251, 25
	v_readlane_b32 s61, v251, 26
	v_readlane_b32 s62, v251, 27
	v_readlane_b32 s63, v251, 28
	v_readlane_b32 s64, v251, 29
	v_readlane_b32 s65, v251, 30
	v_readlane_b32 s66, v251, 31
	v_readlane_b32 s67, v251, 32
	v_readlane_b32 s68, v251, 33
	v_readlane_b32 s69, v251, 34
	v_readlane_b32 s70, v251, 35
	v_readlane_b32 s71, v251, 36
	v_lshl_add_u64 v[16:17], v[16:17], 0, v[0:1]
	s_mov_b64 s[2:3], 0x7800000
	v_readlane_b32 s57, v251, 22
	v_readlane_b32 s58, v251, 23
	v_readlane_b32 s59, v251, 24
	s_mov_b64 s[70:71], s[66:67]
	v_lshl_add_u64 v[110:111], v[16:17], 0, s[2:3]
	s_movk_i32 s2, 0x5c
	s_mov_b64 s[68:69], s[64:65]
	s_mov_b64 s[66:67], s[62:63]
	s_mov_b64 s[64:65], s[60:61]
	v_cmp_gt_i32_e64 s[38:39], s2, v121
	v_lshl_add_u64 v[112:113], v[14:15], 1, s[74:75]
	v_readlane_b32 s2, v248, 8
	v_bfe_u32 v14, v130, 5, 3
	s_add_u32 s0, s64, s0
	v_add_u32_e32 v14, 15, v14
	v_add_u32_e32 v16, s2, v0
	v_lshrrev_b32_e32 v0, 8, v130
	s_addc_u32 s1, s65, s1
	v_lshl_add_u32 v15, v133, 1, s2
	s_movk_i32 s2, 0x420
	v_mad_i32_i24 v139, v0, 23, v14
	v_ashrrev_i32_e32 v0, 3, v131
	s_add_u32 s86, s12, 0x15304000
	v_mul_lo_u32 v138, v121, s2
	v_mul_lo_u32 v17, v131, s2
	v_mul_lo_u32 v19, v132, s2
	v_mad_u64_u32 v[114:115], s[2:3], v0, 23, v[14:15]
	s_addc_u32 s87, s13, 0
	s_lshl_b64 s[2:3], s[46:47], 2
	v_lshlrev_b32_e32 v134, 2, v137
	s_add_u32 s2, s5, s2
	s_addc_u32 s3, s6, s3
	v_lshlrev_b32_e32 v0, 2, v134
	v_lshl_add_u64 v[116:117], s[2:3], 0, v[0:1]
	v_max_i32_e32 v0, 0x4c, v121
	v_sub_u32_e32 v0, v0, v121
	v_add_u32_e32 v0, 15, v0
	v_and_b32_e32 v22, 16, v0
	s_mov_b32 s2, 0xb21642c9
	v_or_b32_e32 v137, s46, v134
	v_cmp_eq_u32_e64 s[46:47], 0, v22
	v_mul_hi_i32 v22, v121, s2
	v_add_u32_e32 v22, v22, v121
	v_lshrrev_b32_e32 v23, 31, v22
	v_ashrrev_i32_e32 v22, 4, v22
	s_movk_i32 s7, 0x210
	v_add_u32_e32 v141, v22, v23
	s_movk_i32 s2, 0xffe9
	v_lshl_add_u32 v136, v133, 2, 0
	v_mul_lo_u32 v20, v121, s7
	v_mul_lo_u32 v14, v131, s7
	v_mul_u32_u24_e32 v21, 0x210, v135
	v_mad_i32_i24 v118, v141, s2, v121
	v_cmp_lt_u32_e64 s[50:51], 15, v0
	v_lshlrev_b32_e32 v0, 5, v18
	v_readlane_b32 s2, v248, 9
	v_readlane_b32 s72, v248, 24
	v_cmp_gt_i32_e64 s[40:41], 47, v121
	v_cmp_gt_i32_e64 s[42:43], 31, v121
	v_cmp_gt_i32_e64 s[44:45], 15, v121
	s_movk_i32 s19, 0x420
	v_add_u32_e32 v140, 15, v121
	v_add_u32_e32 v115, 31, v121
	v_cmp_lt_i32_e64 s[30:31], 14, v118
	v_add_u32_e32 v142, 0x1ff1, v118
	v_ashrrev_i32_e32 v119, 31, v118
	v_add_u32_e32 v120, 0, v0
	v_add_u32_e32 v143, s2, v0
	s_mov_b32 s5, -1
	v_add_u32_e32 v144, v136, v17
	v_add_u32_e32 v145, v136, v19
	v_add_u32_e32 v146, v15, v20
	v_add_u32_e32 v147, v15, v14
	v_add_u32_e32 v146, v146, v20
	v_add_u32_e32 v147, 0x210, v146
	v_add_u32_e32 v140, v140, v121
	v_add_u32_e32 v115, 1, v140
	v_lshrrev_b32_e32 v149, 2, v121
	v_and_b32_e32 v150, 3, v121
	v_lshlrev_b32_e32 v150, 1, v150
	v_mad_u32_u24 v139, v149, 23, v150
	v_add_u32_e32 v139, 15, v139
	v_add_u32_e32 v114, 1, v139
	v_bfe_u32 v118, v133, 6, 1
	v_lshlrev_b32_e32 v118, 4, v118
	v_lshlrev_b32_e32 v119, 1, v118
	v_sub_u32_e32 v119, 16, v119
	v_add_u32_e32 v148, v16, v21
	v_readlane_b32 s2, v249, 36
	v_readlane_b32 s3, v251, 0
	v_readlane_b32 s73, v248, 25
	s_mov_b64 s[62:63], s[58:59]
	s_mov_b64 s[60:61], s[56:57]

; #define LAS __attribute__((address_space(3)))
; __device__ __forceinline__ unsigned pk2(float lo, float hi) { return f2bf(lo) | (f2bf(hi) << 16); }
; __device__ __forceinline__ void mix_phase(LAS unsigned char* lds, const Params& p, const int layer) {
;     ...
;             for (int i = 0; i < 2; ++i) {
;                 const int rl = (tid >> 5) + 16 * i, bi = prt ? rl + 15 : (rl >> 3) * 23 + 15 + (rl & 7), t = (r0 + rl) & 2047;
;                 const LAS float* sp = SL + bi * 264 + q * 8;
;                 const f32x4 u0 = *(const LAS f32x4*)sp, u1 = *(const LAS f32x4*)(sp + 4);
;                 f32x4 s0 = u0, s1 = u1;
; #pragma unroll 4
;                 for (int j = 1; j < w; ++j) { s0 += *(const LAS f32x4*)(sp - j * 264); s1 += *(const LAS f32x4*)(sp - j * 264 + 4); }
;                 const int cnt = (prt && t + 1 < w) ? t + 1 : w; const float inv = 1.0f / (float)cnt;
;                 const f32x4 d0 = s0 * inv - u0, d1 = s1 * inv - u1;
;                 v4u o; o.x = pk2(d0[0], d0[1]); o.y = pk2(d0[2], d0[3]); o.z = pk2(d1[0], d1[1]); o.w = pk2(d1[2], d1[3]);
;                 *(LAS v4u*)(At + rl * 264 + q * 8) = o;
.LBB0_585:
	s_lshl_b32 s13, 2, s12
	s_add_i32 s14, s13, -1
	v_lshl_add_u32 v0, v121, 1, s7
	v_and_b32_e32 v0, 0x7ff, v0
	v_add_u32_e32 v0, 1, v0
	v_min_u32_e32 v0, s13, v0
	v_mov_b32_e32 v149, s13
	v_cndmask_b32_e64 v0, v149, v0, s[52:53]
	v_cvt_f32_ubyte0_e32 v0, v0
	v_div_scale_f32 v149, s[16:17], v0, v0, 1.0
	v_rcp_f32_e32 v150, v149
	s_nop 0
	v_fma_f32 v151, -v149, v150, 1.0
	v_fmac_f32_e32 v150, v151, v150
	v_div_scale_f32 v151, vcc, 1.0, v0, 1.0
	v_mul_f32_e32 v152, v151, v150
	v_fma_f32 v153, -v149, v152, v151
	v_fmac_f32_e32 v152, v153, v150
	v_fma_f32 v149, -v149, v152, v151
	v_div_fmas_f32 v149, v149, v150, v152
	v_div_fixup_f32 v142, v149, v0, 1.0
	v_lshl_add_u32 v0, v121, 1, s7
	v_add_u32_e32 v0, 1, v0
	v_and_b32_e32 v0, 0x7ff, v0
	v_add_u32_e32 v0, 1, v0
	v_min_u32_e32 v0, s13, v0
	v_mov_b32_e32 v149, s13
	v_cndmask_b32_e64 v0, v149, v0, s[52:53]
	v_cvt_f32_ubyte0_e32 v0, v0
	v_div_scale_f32 v149, s[16:17], v0, v0, 1.0
	v_rcp_f32_e32 v150, v149
	s_nop 0
	v_fma_f32 v151, -v149, v150, 1.0
	v_fmac_f32_e32 v150, v151, v150
	v_div_scale_f32 v151, vcc, 1.0, v0, 1.0
	v_mul_f32_e32 v152, v151, v150
	v_fma_f32 v153, -v149, v152, v151
	v_fmac_f32_e32 v152, v153, v150
	v_fma_f32 v149, -v149, v152, v151
	v_div_fmas_f32 v149, v149, v150, v152
	v_div_fixup_f32 v143, v149, v0, 1.0
	v_cndmask_b32_e64 v0, v139, v140, s[52:53]
	v_mul_lo_u32 v0, v0, s19
	v_add_u32_e32 v86, v136, v0
	v_add_u32_e32 v87, v86, v118
	ds_read_b128 v[90:93], v87
	v_add_u32_e32 v87, v87, v119
	ds_read_b128 v[86:89], v87
	v_add_u32_e32 v149, v120, v0
	v_add_u32_e32 v149, v149, v118
	v_add_u32_e32 v141, 0x420, v149
	v_add_u32_e32 v149, 0xfffff7c0, v149
	v_add_u32_e32 v0, v149, v119
	s_lshr_b32 s15, s14, 1
	s_waitcnt lgkmcnt(0)
	v_mov_b64_e32 v[100:101], v[92:93]
	v_mov_b64_e32 v[98:99], v[90:91]
	v_mov_b64_e32 v[96:97], v[88:89]
	v_mov_b64_e32 v[94:95], v[86:87]
	s_cmp_eq_u32 s15, 0
	s_cbranch_scc1 .Lpw_tail_a
.Lpw_pair_a:
	ds_read_b128 v[150:153], v149 offset:1056
	ds_read_b128 v[154:157], v0 offset:1056
	ds_read_b128 v[158:161], v149
	ds_read_b128 v[252:255], v0
	s_add_i32 s15, s15, -1
	v_add_u32_e32 v149, 0xfffff7c0, v149
	v_add_u32_e32 v0, 0xfffff7c0, v0
	s_cmp_lg_u32 s15, 0
	s_waitcnt lgkmcnt(2)
	v_pk_add_f32 v[100:101], v[100:101], v[152:153]
	v_pk_add_f32 v[98:99], v[98:99], v[150:151]
	v_pk_add_f32 v[96:97], v[96:97], v[156:157]
	v_pk_add_f32 v[94:95], v[94:95], v[154:155]
	s_waitcnt lgkmcnt(0)
	v_pk_add_f32 v[100:101], v[100:101], v[160:161]
	v_pk_add_f32 v[98:99], v[98:99], v[158:159]
	v_pk_add_f32 v[96:97], v[96:97], v[254:255]
	v_pk_add_f32 v[94:95], v[94:95], v[252:253]
	s_cbranch_scc1 .Lpw_pair_a
.Lpw_tail_a:
	ds_read_b128 v[150:153], v149 offset:1056
	ds_read_b128 v[154:157], v0 offset:1056
	v_add_u32_e32 v0, v141, v119
	ds_read_b128 v[158:161], v141
	ds_read_b128 v[252:255], v0
	s_waitcnt lgkmcnt(2)
	v_pk_add_f32 v[100:101], v[100:101], v[152:153]
	v_pk_add_f32 v[98:99], v[98:99], v[150:151]
	v_pk_add_f32 v[96:97], v[96:97], v[156:157]
	v_pk_add_f32 v[94:95], v[94:95], v[154:155]
	v_mov_b32_e32 v0, v142
	v_pk_fma_f32 v[90:91], v[0:1], v[98:99], v[90:91] op_sel_hi:[0,1,1] neg_lo:[0,0,1] neg_hi:[0,0,1]
	v_pk_fma_f32 v[92:93], v[0:1], v[100:101], v[92:93] op_sel_hi:[0,1,1] neg_lo:[0,0,1] neg_hi:[0,0,1]
	v_pk_fma_f32 v[86:87], v[0:1], v[94:95], v[86:87] op_sel_hi:[0,1,1] neg_lo:[0,0,1] neg_hi:[0,0,1]
	v_pk_fma_f32 v[88:89], v[0:1], v[96:97], v[88:89] op_sel_hi:[0,1,1] neg_lo:[0,0,1] neg_hi:[0,0,1]
	v_cvt_pk_bf16_f32 v90, v90, v91
	v_cvt_pk_bf16_f32 v91, v92, v93
	v_cvt_pk_bf16_f32 v92, v86, v87
	v_cvt_pk_bf16_f32 v93, v88, v89
	v_lshrrev_b32_e32 v0, 1, v118
	v_add_u32_e32 v149, v146, v0
	v_ashrrev_i32_e32 v0, 1, v119
	v_add_u32_e32 v0, v149, v0
	ds_write_b64 v149, v[90:91]
	ds_write_b64 v0, v[92:93]
	s_waitcnt lgkmcnt(2)
	v_pk_add_f32 v[98:99], v[98:99], v[158:159]
	v_pk_add_f32 v[100:101], v[100:101], v[160:161]
	v_pk_add_f32 v[94:95], v[94:95], v[252:253]
	v_pk_add_f32 v[96:97], v[96:97], v[254:255]
	v_pk_add_f32 v[98:99], v[98:99], v[150:151] neg_lo:[0,1] neg_hi:[0,1]
	v_pk_add_f32 v[100:101], v[100:101], v[152:153] neg_lo:[0,1] neg_hi:[0,1]
	v_pk_add_f32 v[94:95], v[94:95], v[154:155] neg_lo:[0,1] neg_hi:[0,1]
	v_pk_add_f32 v[96:97], v[96:97], v[156:157] neg_lo:[0,1] neg_hi:[0,1]
	v_mov_b32_e32 v0, v143
	v_pk_fma_f32 v[158:159], v[0:1], v[98:99], v[158:159] op_sel_hi:[0,1,1] neg_lo:[0,0,1] neg_hi:[0,0,1]
	v_pk_fma_f32 v[160:161], v[0:1], v[100:101], v[160:161] op_sel_hi:[0,1,1] neg_lo:[0,0,1] neg_hi:[0,0,1]
	v_pk_fma_f32 v[252:253], v[0:1], v[94:95], v[252:253] op_sel_hi:[0,1,1] neg_lo:[0,0,1] neg_hi:[0,0,1]
	v_pk_fma_f32 v[254:255], v[0:1], v[96:97], v[254:255] op_sel_hi:[0,1,1] neg_lo:[0,0,1] neg_hi:[0,0,1]
	v_cvt_pk_bf16_f32 v158, v158, v159
	v_cvt_pk_bf16_f32 v159, v160, v161
	v_cvt_pk_bf16_f32 v160, v252, v253
	v_cvt_pk_bf16_f32 v161, v254, v255
	v_lshrrev_b32_e32 v0, 1, v118
	v_add_u32_e32 v149, v147, v0
	v_ashrrev_i32_e32 v0, 1, v119
	v_add_u32_e32 v0, v149, v0
	ds_write_b64 v149, v[158:159]
	ds_write_b64 v0, v[160:161]
	s_waitcnt lgkmcnt(0)
	s_barrier
; #define LAS __attribute__((address_space(3)))
; __device__ __forceinline__ unsigned pk2(float lo, float hi) { return f2bf(lo) | (f2bf(hi) << 16); }
; __device__ __forceinline__ float bflo(unsigned w) { return __uint_as_float(w << 16); }
; __device__ __forceinline__ float bfhi(unsigned w) { return __uint_as_float(w & 0xffff0000u); }
; __device__ __forceinline__ void mix_phase(LAS unsigned char* lds, const Params& p, const int layer) {
;     ...
;             __syncthreads();
;             f32x4 acc[2][2];
; #pragma unroll
;             for (int m = 0; m < 2; ++m)
; #pragma unroll
;                 for (int n = 0; n < 2; ++n) acc[m][n] = (f32x4){0.f, 0.f, 0.f, 0.f};
; #pragma unroll
;             for (int ks = 0; ks < 8; ++ks) {
;                 bf16x8 a[2];
; #pragma unroll
;                 for (int m = 0; m < 2; ++m) a[m] = *(const LAS bf16x8*)(At + (m * 16 + fr) * 264 + ks * 32 + fq * 8);
; #pragma unroll
;                 for (int m = 0; m < 2; ++m)
; #pragma unroll
;                     for (int n = 0; n < 2; ++n) acc[m][n] = __builtin_amdgcn_mfma_f32_16x16x32_bf16(b[n][ks], a[m], acc[m][n], 0, 0, 0);
;             }
;             bf16* YA = (bf16*)(ws + WS_YA);
; #pragma unroll
;             for (int m = 0; m < 2; ++m)
; #pragma unroll
;                 for (int n = 0; n < 2; ++n) { const int r = r0 + m * 16 + fr, ch = g * 256 + wid * 32 + n * 16 + fq * 4; const v2u sg = sgc[m][n];
;                     const f32x4 y = acc[m][n] * ps[n] * (f32x4){bflo(sg.x), bfhi(sg.x), bflo(sg.y), bfhi(sg.y)};
;                     v2u o; o.x = pk2(y[0], y[1]); o.y = pk2(y[2], y[3]); *(v2u*)(YA + (size_t)r * KCAT + ch) = o; }
	ds_read_b128 v[86:89], v148
	ds_read_b128 v[90:93], v148 offset:8448
	ds_read_b128 v[150:153], v148 offset:64
	ds_read_b128 v[154:157], v148 offset:8512
	s_waitcnt lgkmcnt(0)
	s_waitcnt vmcnt(15)
	v_mfma_f32_16x16x32_bf16 v[94:97], v[42:45], v[86:89], 0
	v_or_b32_e32 v0, s7, v135
	s_movk_i32 s12, 0x1800
	s_and_b64 vcc, exec, s[90:91]
	v_mfma_f32_16x16x32_bf16 v[86:89], v[74:77], v[86:89], 0
	v_mfma_f32_16x16x32_bf16 v[98:101], v[42:45], v[90:93], 0
	v_mfma_f32_16x16x32_bf16 v[90:93], v[74:77], v[90:93], 0
	v_mfma_f32_16x16x32_bf16 v[94:97], v[38:41], v[150:153], v[94:97]
	v_mfma_f32_16x16x32_bf16 v[86:89], v[70:73], v[150:153], v[86:89]
	v_mfma_f32_16x16x32_bf16 v[98:101], v[38:41], v[154:157], v[98:101]
	v_mfma_f32_16x16x32_bf16 v[90:93], v[70:73], v[154:157], v[90:93]
	ds_read_b128 v[150:153], v148 offset:128
	ds_read_b128 v[154:157], v148 offset:8576
	s_waitcnt lgkmcnt(1)
	v_mfma_f32_16x16x32_bf16 v[94:97], v[34:37], v[150:153], v[94:97]
	v_mfma_f32_16x16x32_bf16 v[86:89], v[66:69], v[150:153], v[86:89]
	s_waitcnt lgkmcnt(0)
	v_mfma_f32_16x16x32_bf16 v[98:101], v[34:37], v[154:157], v[98:101]
	v_mfma_f32_16x16x32_bf16 v[90:93], v[66:69], v[154:157], v[90:93]
	ds_read_b128 v[150:153], v148 offset:192
	ds_read_b128 v[154:157], v148 offset:8640
	s_waitcnt lgkmcnt(1)
	v_mfma_f32_16x16x32_bf16 v[94:97], v[30:33], v[150:153], v[94:97]
	s_waitcnt vmcnt(10)
	v_mfma_f32_16x16x32_bf16 v[86:89], v[62:65], v[150:153], v[86:89]
	s_waitcnt lgkmcnt(0)
	v_mfma_f32_16x16x32_bf16 v[98:101], v[30:33], v[154:157], v[98:101]
	v_mfma_f32_16x16x32_bf16 v[90:93], v[62:65], v[154:157], v[90:93]
	ds_read_b128 v[150:153], v148 offset:256
	ds_read_b128 v[154:157], v148 offset:8704
	s_waitcnt lgkmcnt(1)
	v_mfma_f32_16x16x32_bf16 v[94:97], v[26:29], v[150:153], v[94:97]
	v_mfma_f32_16x16x32_bf16 v[86:89], v[58:61], v[150:153], v[86:89]
	s_waitcnt lgkmcnt(0)
	v_mfma_f32_16x16x32_bf16 v[98:101], v[26:29], v[154:157], v[98:101]
	v_mfma_f32_16x16x32_bf16 v[90:93], v[58:61], v[154:157], v[90:93]
	ds_read_b128 v[150:153], v148 offset:320
	ds_read_b128 v[154:157], v148 offset:8768
	s_waitcnt lgkmcnt(1)
	v_mfma_f32_16x16x32_bf16 v[94:97], v[22:25], v[150:153], v[94:97]
	v_mfma_f32_16x16x32_bf16 v[86:89], v[54:57], v[150:153], v[86:89]
	s_waitcnt lgkmcnt(0)
	v_mfma_f32_16x16x32_bf16 v[98:101], v[22:25], v[154:157], v[98:101]
	v_mfma_f32_16x16x32_bf16 v[90:93], v[54:57], v[154:157], v[90:93]
	ds_read_b128 v[150:153], v148 offset:384
	ds_read_b128 v[154:157], v148 offset:8832
	s_waitcnt lgkmcnt(1)
	v_mfma_f32_16x16x32_bf16 v[94:97], v[18:21], v[150:153], v[94:97]
	v_mfma_f32_16x16x32_bf16 v[86:89], v[50:53], v[150:153], v[86:89]
	s_waitcnt lgkmcnt(0)
	v_mfma_f32_16x16x32_bf16 v[98:101], v[18:21], v[154:157], v[98:101]
	v_mfma_f32_16x16x32_bf16 v[90:93], v[50:53], v[154:157], v[90:93]
	ds_read_b128 v[150:153], v148 offset:448
	ds_read_b128 v[154:157], v148 offset:8896
	s_waitcnt lgkmcnt(1)
	v_mfma_f32_16x16x32_bf16 v[94:97], v[14:17], v[150:153], v[94:97]
	s_waitcnt lgkmcnt(0)
	v_mfma_f32_16x16x32_bf16 v[98:101], v[14:17], v[154:157], v[98:101]
	s_nop 5
	v_mul_f32_e64 v94, v82, v94
	v_mul_f32_e64 v95, v83, v95
	v_pk_mul_f32 v[96:97], v[84:85], v[96:97]
	v_mfma_f32_16x16x32_bf16 v[90:93], v[46:49], v[154:157], v[90:93]
	s_waitcnt vmcnt(7)
	v_lshlrev_b32_e32 v156, 16, v108
	v_and_b32_e32 v157, 0xffff0000, v108
	v_lshlrev_b32_e32 v108, 16, v109
	v_and_b32_e32 v109, 0xffff0000, v109
	v_pk_mul_f32 v[94:95], v[94:95], v[156:157]
	v_pk_mul_f32 v[96:97], v[96:97], v[108:109]
	v_bfe_u32 v108, v94, 16, 1
	v_add3_u32 v94, v94, v108, s26
	v_bfe_u32 v108, v95, 16, 1
	v_lshrrev_b32_e32 v94, 16, v94
	v_add3_u32 v95, v95, v108, s26
	v_and_or_b32 v94, v95, s24, v94
	v_bfe_u32 v95, v96, 16, 1
	v_mfma_f32_16x16x32_bf16 v[86:89], v[46:49], v[150:153], v[86:89]
	v_add_u32_e32 v150, s6, v137
	v_add3_u32 v95, v96, v95, s26
	v_bfe_u32 v96, v97, 16, 1
	v_mov_b64_e32 v[152:153], s[86:87]
	v_lshrrev_b32_e32 v95, 16, v95
	v_add3_u32 v96, v97, v96, s26
	v_ashrrev_i32_e32 v151, 31, v150
	v_mad_i64_i32 v[154:155], s[6:7], v0, s12, v[152:153]
	v_and_or_b32 v95, v96, s24, v95
	v_lshlrev_b64 v[96:97], 1, v[150:151]
	v_lshl_add_u64 v[108:109], v[154:155], 0, v[96:97]
	global_store_dwordx2 v[108:109], v[94:95], off
	v_pk_mul_f32 v[86:87], v[78:79], v[86:87]
	s_waitcnt vmcnt(5)
	v_lshlrev_b32_e32 v94, 16, v106
	v_and_b32_e32 v95, 0xffff0000, v106
	v_pk_mul_f32 v[86:87], v[86:87], v[94:95]
	v_pk_mul_f32 v[88:89], v[80:81], v[88:89]
	v_bfe_u32 v94, v86, 16, 1
	v_lshlrev_b32_e32 v106, 16, v107
	v_and_b32_e32 v107, 0xffff0000, v107
	v_add3_u32 v86, v86, v94, s26
	v_bfe_u32 v94, v87, 16, 1
	v_pk_mul_f32 v[88:89], v[88:89], v[106:107]
	v_lshrrev_b32_e32 v86, 16, v86
	v_add3_u32 v87, v87, v94, s26
	v_and_or_b32 v86, v87, s24, v86
	v_bfe_u32 v87, v88, 16, 1
	v_add3_u32 v87, v88, v87, s26
	v_bfe_u32 v88, v89, 16, 1
	v_lshrrev_b32_e32 v87, 16, v87
	v_add3_u32 v88, v89, v88, s26
	v_pk_mul_f32 v[94:95], v[82:83], v[98:99]
	v_lshlrev_b32_e32 v98, 16, v104
	v_and_b32_e32 v99, 0xffff0000, v104
	v_and_or_b32 v87, v88, s24, v87
	v_or_b32_e32 v0, 16, v0
	v_pk_mul_f32 v[94:95], v[94:95], v[98:99]
	global_store_dwordx2 v[108:109], v[86:87], off offset:32
	v_mad_i64_i32 v[86:87], s[6:7], v0, s12, v[152:153]
	v_bfe_u32 v0, v94, 16, 1
	v_pk_mul_f32 v[88:89], v[84:85], v[100:101]
	v_lshlrev_b32_e32 v100, 16, v105
	v_and_b32_e32 v101, 0xffff0000, v105
	v_add3_u32 v0, v94, v0, s26
	v_bfe_u32 v94, v95, 16, 1
	v_pk_mul_f32 v[88:89], v[88:89], v[100:101]
	v_lshrrev_b32_e32 v0, 16, v0
	v_add3_u32 v94, v95, v94, s26
	v_and_or_b32 v94, v94, s24, v0
	v_bfe_u32 v0, v88, 16, 1
	v_add3_u32 v0, v88, v0, s26
	v_bfe_u32 v88, v89, 16, 1
	v_lshrrev_b32_e32 v0, 16, v0
	v_add3_u32 v88, v89, v88, s26
	v_and_or_b32 v95, v88, s24, v0
	v_pk_mul_f32 v[88:89], v[80:81], v[92:93]
	v_pk_mul_f32 v[90:91], v[78:79], v[90:91]
	v_lshlrev_b32_e32 v92, 16, v102
	v_and_b32_e32 v93, 0xffff0000, v102
	v_pk_mul_f32 v[90:91], v[90:91], v[92:93]
	v_lshl_add_u64 v[86:87], v[86:87], 0, v[96:97]
	v_bfe_u32 v0, v90, 16, 1
	global_store_dwordx2 v[86:87], v[94:95], off
	v_lshlrev_b32_e32 v94, 16, v103
	v_and_b32_e32 v95, 0xffff0000, v103
	v_add3_u32 v0, v90, v0, s26
	v_bfe_u32 v90, v91, 16, 1
	v_pk_mul_f32 v[88:89], v[88:89], v[94:95]
	v_lshrrev_b32_e32 v0, 16, v0
	v_add3_u32 v90, v91, v90, s26
	v_and_or_b32 v90, v90, s24, v0
	v_bfe_u32 v0, v88, 16, 1
	v_add3_u32 v0, v88, v0, s26
	v_bfe_u32 v88, v89, 16, 1
	v_lshrrev_b32_e32 v0, 16, v0
	v_add3_u32 v88, v89, v88, s26
	v_readlane_b32 s6, v249, 62
	v_and_or_b32 v91, v88, s24, v0
	s_add_i32 s2, s2, s6
	s_waitcnt vmcnt(4)
	v_mov_b64_e32 v[102:103], v[126:127]
	v_mov_b64_e32 v[104:105], v[124:125]
	s_waitcnt vmcnt(3)
	v_mov_b64_e32 v[106:107], v[128:129]
	v_mov_b64_e32 v[108:109], v[122:123]
	global_store_dwordx2 v[86:87], v[90:91], off offset:32
	s_cbranch_vccz .LBB0_551

;     __device__ __forceinline__ void hook(f32x4 (&acc)[2][2][4][2], const Unit& u, int wr, int wc, int fr, int fq) const {
;         int row0 = u.pm * BM + wr * 64 + fr, col0 = u.pn * BM + wc * 32 + 8 * fq;
;         asm volatile("" : "+v"(row0), "+v"(col0));
;         u32x4 ga[2][2], gb[2][2];
; #pragma unroll
;         for (int bj = 0; bj < 2; ++bj) { const bf16_t* gp = G + (size_t)row0 * ldg + col0 + bj * HALF; ga[0][bj] = *(const u32x4*)(gp + 6144); gb[0][bj] = *(const u32x4*)(gp + 8192); }
; #pragma unroll
;         for (int g = 0; g < 8; ++g) { const int ai = g >> 2, m = g & 3, cb = g & 1, nb_ = cb ^ 1;
;             if (g < 7) { const int an = (g + 1) >> 2, mn = (g + 1) & 3;
; #pragma unroll
;                 for (int bj = 0; bj < 2; ++bj) { const bf16_t* gp = G + (size_t)(row0 + an * HALF + mn * 16) * ldg + col0 + bj * HALF; ga[nb_][bj] = *(const u32x4*)(gp + 6144); gb[nb_][bj] = *(const u32x4*)(gp + 8192); } }
; #pragma unroll
;             for (int bj = 0; bj < 2; ++bj) { f32x4 a0, a1, b0, b1; unpack_bf16x8(ga[cb][bj], a0, a1); unpack_bf16x8(gb[cb][bj], b0, b1);
; #pragma unroll
;                 for (int j = 0; j < 4; ++j) { a0[j] = a0[j] * __builtin_amdgcn_rcpf(fmaxf(b0[j], 1e-30f)); a1[j] = a1[j] * __builtin_amdgcn_rcpf(fmaxf(b1[j], 1e-30f)); }
;                 acc[ai][bj][m][0] = acc[ai][bj][m][0] * a0; acc[ai][bj][m][1] = acc[ai][bj][m][1] * a1; }
;             asm volatile("" ::: "memory"); }
.LBB0_755:
	s_cmpk_eq_i32 s90, 0x800
	s_cselect_b64 s[92:93], -1, 0
	s_and_b64 s[92:93], s[38:39], s[92:93]
	s_andn2_b64 vcc, exec, s[92:93]
	s_cbranch_vccnz .LBB0_754
	v_mul_u32_u24_e32 v2, 0x5000, v180
	v_lshl_add_u32 v2, v182, 1, v2
	s_add_u32 s98, s8, 0x3000
	s_addc_u32 s99, s9, 0
	s_add_u32 s100, s8, 0x4000
	s_addc_u32 s101, s9, 0
	s_nop 1
	global_load_dwordx4 v[132:135], v2, s[98:99] nt
	global_load_dwordx4 v[136:139], v2, s[100:101]
	global_load_dwordx4 v[140:143], v2, s[98:99] offset:256 nt
	global_load_dwordx4 v[144:147], v2, s[100:101] offset:256
	v_add_u32_e32 v2, 0x50000, v2
	global_load_dwordx4 v[148:151], v2, s[98:99] nt
	global_load_dwordx4 v[152:155], v2, s[100:101]
	global_load_dwordx4 v[156:159], v2, s[98:99] offset:256 nt
	global_load_dwordx4 v[160:163], v2, s[100:101] offset:256
	v_add_u32_e32 v2, 0x50000, v2
	global_load_dwordx4 v[196:199], v2, s[98:99] nt
	global_load_dwordx4 v[210:213], v2, s[100:101]
	global_load_dwordx4 v[224:227], v2, s[98:99] offset:256 nt
	global_load_dwordx4 v[228:231], v2, s[100:101] offset:256
	v_add_u32_e32 v2, 0x50000, v2
	global_load_dwordx4 v[232:235], v2, s[98:99] nt
	global_load_dwordx4 v[236:239], v2, s[100:101]
	global_load_dwordx4 v[240:243], v2, s[98:99] offset:256 nt
	global_load_dwordx4 v[244:247], v2, s[100:101] offset:256
	v_add_u32_e32 v2, 0x190000, v2
	s_waitcnt vmcnt(14)
	v_lshlrev_b32_e32 v188, 16, v136
	v_and_b32_e32 v189, 0xffff0000, v136
	v_lshlrev_b32_e32 v200, 16, v137
	v_and_b32_e32 v201, 0xffff0000, v137
	v_max_f32_e32 v188, v188, v188
	v_max_f32_e32 v189, v189, v189
	v_max_f32_e32 v200, v200, v200
	v_max_f32_e32 v201, v201, v201
	v_max_f32_e32 v188, 0xda24260, v188
	v_max_f32_e32 v189, 0xda24260, v189
	v_max_f32_e32 v200, 0xda24260, v200
	v_max_f32_e32 v201, 0xda24260, v201
	v_rcp_f32_e32 v188, v188
	v_rcp_f32_e32 v189, v189
	v_rcp_f32_e32 v200, v200
	v_rcp_f32_e32 v201, v201
	v_lshlrev_b32_e32 v204, 16, v132
	v_and_b32_e32 v205, 0xffff0000, v132
	v_lshlrev_b32_e32 v214, 16, v133
	v_and_b32_e32 v215, 0xffff0000, v133
	v_pk_mul_f32 v[188:189], v[188:189], v[204:205]
	v_pk_mul_f32 v[200:201], v[200:201], v[214:215]
	v_pk_mul_f32 v[120:121], v[120:121], v[188:189]
	v_pk_mul_f32 v[122:123], v[122:123], v[200:201]
	v_lshlrev_b32_e32 v188, 16, v138
	v_and_b32_e32 v189, 0xffff0000, v138
	v_lshlrev_b32_e32 v200, 16, v139
	v_and_b32_e32 v201, 0xffff0000, v139
	v_max_f32_e32 v188, v188, v188
	v_max_f32_e32 v189, v189, v189
	v_max_f32_e32 v200, v200, v200
	v_max_f32_e32 v201, v201, v201
	v_max_f32_e32 v188, 0xda24260, v188
	v_max_f32_e32 v189, 0xda24260, v189
	v_max_f32_e32 v200, 0xda24260, v200
	v_max_f32_e32 v201, 0xda24260, v201
	v_rcp_f32_e32 v188, v188
	v_rcp_f32_e32 v189, v189
	v_rcp_f32_e32 v200, v200
	v_rcp_f32_e32 v201, v201
	v_lshlrev_b32_e32 v204, 16, v134
	v_and_b32_e32 v205, 0xffff0000, v134
	v_lshlrev_b32_e32 v214, 16, v135
	v_and_b32_e32 v215, 0xffff0000, v135
	v_pk_mul_f32 v[188:189], v[188:189], v[204:205]
	v_pk_mul_f32 v[200:201], v[200:201], v[214:215]
	v_pk_mul_f32 v[116:117], v[116:117], v[188:189]
	v_pk_mul_f32 v[118:119], v[118:119], v[200:201]
	s_waitcnt vmcnt(12)
	v_lshlrev_b32_e32 v188, 16, v144
	v_and_b32_e32 v189, 0xffff0000, v144
	v_lshlrev_b32_e32 v200, 16, v145
	v_and_b32_e32 v201, 0xffff0000, v145
	v_max_f32_e32 v188, v188, v188
	v_max_f32_e32 v189, v189, v189
	v_max_f32_e32 v200, v200, v200
	v_max_f32_e32 v201, v201, v201
	v_max_f32_e32 v188, 0xda24260, v188
	v_max_f32_e32 v189, 0xda24260, v189
	v_max_f32_e32 v200, 0xda24260, v200
	v_max_f32_e32 v201, 0xda24260, v201
	v_rcp_f32_e32 v188, v188
	v_rcp_f32_e32 v189, v189
	v_rcp_f32_e32 v200, v200
	v_rcp_f32_e32 v201, v201
	v_lshlrev_b32_e32 v204, 16, v140
	v_and_b32_e32 v205, 0xffff0000, v140
	v_lshlrev_b32_e32 v214, 16, v141
	v_and_b32_e32 v215, 0xffff0000, v141
	v_pk_mul_f32 v[188:189], v[188:189], v[204:205]
	v_pk_mul_f32 v[200:201], v[200:201], v[214:215]
	v_pk_mul_f32 v[128:129], v[128:129], v[188:189]
	v_pk_mul_f32 v[130:131], v[130:131], v[200:201]
	v_lshlrev_b32_e32 v188, 16, v146
	v_and_b32_e32 v189, 0xffff0000, v146
	v_lshlrev_b32_e32 v200, 16, v147
	v_and_b32_e32 v201, 0xffff0000, v147
	v_max_f32_e32 v188, v188, v188
	v_max_f32_e32 v189, v189, v189
	v_max_f32_e32 v200, v200, v200
	v_max_f32_e32 v201, v201, v201
	v_max_f32_e32 v188, 0xda24260, v188
	v_max_f32_e32 v189, 0xda24260, v189
	v_max_f32_e32 v200, 0xda24260, v200
	v_max_f32_e32 v201, 0xda24260, v201
	v_rcp_f32_e32 v188, v188
	v_rcp_f32_e32 v189, v189
	v_rcp_f32_e32 v200, v200
	v_rcp_f32_e32 v201, v201
	v_lshlrev_b32_e32 v204, 16, v142
	v_and_b32_e32 v205, 0xffff0000, v142
	v_lshlrev_b32_e32 v214, 16, v143
	v_and_b32_e32 v215, 0xffff0000, v143
	v_pk_mul_f32 v[188:189], v[188:189], v[204:205]
	v_pk_mul_f32 v[200:201], v[200:201], v[214:215]
	v_pk_mul_f32 v[124:125], v[124:125], v[188:189]
	v_pk_mul_f32 v[126:127], v[126:127], v[200:201]
	global_load_dwordx4 v[132:135], v2, s[98:99] nt
	global_load_dwordx4 v[136:139], v2, s[100:101]
	global_load_dwordx4 v[140:143], v2, s[98:99] offset:256 nt
	global_load_dwordx4 v[144:147], v2, s[100:101] offset:256
	v_add_u32_e32 v2, 0x50000, v2
	s_waitcnt vmcnt(14)
;     __device__ __forceinline__ void hook(f32x4 (&acc)[2][2][4][2], const Unit& u, int wr, int wc, int fr, int fq) const {
;     ...
;         for (int g = 0; g < 8; ++g) { const int ai = g >> 2, m = g & 3, cb = g & 1, nb_ = cb ^ 1;
;             if (g < 7) { const int an = (g + 1) >> 2, mn = (g + 1) & 3;
; #pragma unroll
;                 for (int bj = 0; bj < 2; ++bj) { const bf16_t* gp = G + (size_t)(row0 + an * HALF + mn * 16) * ldg + col0 + bj * HALF; ga[nb_][bj] = *(const u32x4*)(gp + 6144); gb[nb_][bj] = *(const u32x4*)(gp + 8192); } }
; #pragma unroll
;             for (int bj = 0; bj < 2; ++bj) { f32x4 a0, a1, b0, b1; unpack_bf16x8(ga[cb][bj], a0, a1); unpack_bf16x8(gb[cb][bj], b0, b1);
; #pragma unroll
;                 for (int j = 0; j < 4; ++j) { a0[j] = a0[j] * __builtin_amdgcn_rcpf(fmaxf(b0[j], 1e-30f)); a1[j] = a1[j] * __builtin_amdgcn_rcpf(fmaxf(b1[j], 1e-30f)); }
;                 acc[ai][bj][m][0] = acc[ai][bj][m][0] * a0; acc[ai][bj][m][1] = acc[ai][bj][m][1] * a1; }
;             asm volatile("" ::: "memory"); }
	v_lshlrev_b32_e32 v188, 16, v152
	v_and_b32_e32 v189, 0xffff0000, v152
	v_lshlrev_b32_e32 v200, 16, v153
	v_and_b32_e32 v201, 0xffff0000, v153
	v_max_f32_e32 v188, v188, v188
	v_max_f32_e32 v189, v189, v189
	v_max_f32_e32 v200, v200, v200
	v_max_f32_e32 v201, v201, v201
	v_max_f32_e32 v188, 0xda24260, v188
	v_max_f32_e32 v189, 0xda24260, v189
	v_max_f32_e32 v200, 0xda24260, v200
	v_max_f32_e32 v201, 0xda24260, v201
	v_rcp_f32_e32 v188, v188
	v_rcp_f32_e32 v189, v189
	v_rcp_f32_e32 v200, v200
	v_rcp_f32_e32 v201, v201
	v_lshlrev_b32_e32 v204, 16, v148
	v_and_b32_e32 v205, 0xffff0000, v148
	v_lshlrev_b32_e32 v214, 16, v149
	v_and_b32_e32 v215, 0xffff0000, v149
	v_pk_mul_f32 v[188:189], v[188:189], v[204:205]
	v_pk_mul_f32 v[200:201], v[200:201], v[214:215]
	v_pk_mul_f32 v[112:113], v[112:113], v[188:189]
	v_pk_mul_f32 v[114:115], v[114:115], v[200:201]
	v_lshlrev_b32_e32 v188, 16, v154
	v_and_b32_e32 v189, 0xffff0000, v154
	v_lshlrev_b32_e32 v200, 16, v155
	v_and_b32_e32 v201, 0xffff0000, v155
	v_max_f32_e32 v188, v188, v188
	v_max_f32_e32 v189, v189, v189
	v_max_f32_e32 v200, v200, v200
	v_max_f32_e32 v201, v201, v201
	v_max_f32_e32 v188, 0xda24260, v188
	v_max_f32_e32 v189, 0xda24260, v189
	v_max_f32_e32 v200, 0xda24260, v200
	v_max_f32_e32 v201, 0xda24260, v201
	v_rcp_f32_e32 v188, v188
	v_rcp_f32_e32 v189, v189
	v_rcp_f32_e32 v200, v200
	v_rcp_f32_e32 v201, v201
	v_lshlrev_b32_e32 v204, 16, v150
	v_and_b32_e32 v205, 0xffff0000, v150
	v_lshlrev_b32_e32 v214, 16, v151
	v_and_b32_e32 v215, 0xffff0000, v151
	v_pk_mul_f32 v[188:189], v[188:189], v[204:205]
	v_pk_mul_f32 v[200:201], v[200:201], v[214:215]
	v_pk_mul_f32 v[108:109], v[108:109], v[188:189]
	v_pk_mul_f32 v[110:111], v[110:111], v[200:201]
	s_waitcnt vmcnt(12)
	v_lshlrev_b32_e32 v188, 16, v160
	v_and_b32_e32 v189, 0xffff0000, v160
	v_lshlrev_b32_e32 v200, 16, v161
	v_and_b32_e32 v201, 0xffff0000, v161
	v_max_f32_e32 v188, v188, v188
	v_max_f32_e32 v189, v189, v189
	v_max_f32_e32 v200, v200, v200
	v_max_f32_e32 v201, v201, v201
	v_max_f32_e32 v188, 0xda24260, v188
	v_max_f32_e32 v189, 0xda24260, v189
	v_max_f32_e32 v200, 0xda24260, v200
	v_max_f32_e32 v201, 0xda24260, v201
	v_rcp_f32_e32 v188, v188
	v_rcp_f32_e32 v189, v189
	v_rcp_f32_e32 v200, v200
	v_rcp_f32_e32 v201, v201
	v_lshlrev_b32_e32 v204, 16, v156
	v_and_b32_e32 v205, 0xffff0000, v156
	v_lshlrev_b32_e32 v214, 16, v157
	v_and_b32_e32 v215, 0xffff0000, v157
	v_pk_mul_f32 v[188:189], v[188:189], v[204:205]
	v_pk_mul_f32 v[200:201], v[200:201], v[214:215]
	v_pk_mul_f32 v[104:105], v[104:105], v[188:189]
	v_pk_mul_f32 v[106:107], v[106:107], v[200:201]
	v_lshlrev_b32_e32 v188, 16, v162
	v_and_b32_e32 v189, 0xffff0000, v162
	v_lshlrev_b32_e32 v200, 16, v163
	v_and_b32_e32 v201, 0xffff0000, v163
	v_max_f32_e32 v188, v188, v188
	v_max_f32_e32 v189, v189, v189
	v_max_f32_e32 v200, v200, v200
	v_max_f32_e32 v201, v201, v201
	v_max_f32_e32 v188, 0xda24260, v188
	v_max_f32_e32 v189, 0xda24260, v189
	v_max_f32_e32 v200, 0xda24260, v200
	v_max_f32_e32 v201, 0xda24260, v201
	v_rcp_f32_e32 v188, v188
	v_rcp_f32_e32 v189, v189
	v_rcp_f32_e32 v200, v200
	v_rcp_f32_e32 v201, v201
	v_lshlrev_b32_e32 v204, 16, v158
	v_and_b32_e32 v205, 0xffff0000, v158
	v_lshlrev_b32_e32 v214, 16, v159
	v_and_b32_e32 v215, 0xffff0000, v159
	v_pk_mul_f32 v[188:189], v[188:189], v[204:205]
	v_pk_mul_f32 v[200:201], v[200:201], v[214:215]
	v_pk_mul_f32 v[100:101], v[100:101], v[188:189]
	v_pk_mul_f32 v[102:103], v[102:103], v[200:201]
	global_load_dwordx4 v[148:151], v2, s[98:99] nt
	global_load_dwordx4 v[152:155], v2, s[100:101]
	global_load_dwordx4 v[156:159], v2, s[98:99] offset:256 nt
	global_load_dwordx4 v[160:163], v2, s[100:101] offset:256
	v_add_u32_e32 v2, 0x50000, v2
	s_waitcnt vmcnt(14)
	v_lshlrev_b32_e32 v188, 16, v210
	v_and_b32_e32 v189, 0xffff0000, v210
	v_lshlrev_b32_e32 v200, 16, v211
	v_and_b32_e32 v201, 0xffff0000, v211
	v_max_f32_e32 v188, v188, v188
	v_max_f32_e32 v189, v189, v189
	v_max_f32_e32 v200, v200, v200
	v_max_f32_e32 v201, v201, v201
	v_max_f32_e32 v188, 0xda24260, v188
	v_max_f32_e32 v189, 0xda24260, v189
	v_max_f32_e32 v200, 0xda24260, v200
	v_max_f32_e32 v201, 0xda24260, v201
	v_rcp_f32_e32 v188, v188
	v_rcp_f32_e32 v189, v189
	v_rcp_f32_e32 v200, v200
	v_rcp_f32_e32 v201, v201
	v_lshlrev_b32_e32 v204, 16, v196
	v_and_b32_e32 v205, 0xffff0000, v196
	v_lshlrev_b32_e32 v214, 16, v197
	v_and_b32_e32 v215, 0xffff0000, v197
	v_pk_mul_f32 v[188:189], v[188:189], v[204:205]
	v_pk_mul_f32 v[200:201], v[200:201], v[214:215]
	v_pk_mul_f32 v[96:97], v[96:97], v[188:189]
	v_pk_mul_f32 v[98:99], v[98:99], v[200:201]
	v_lshlrev_b32_e32 v188, 16, v212
	v_and_b32_e32 v189, 0xffff0000, v212
	v_lshlrev_b32_e32 v200, 16, v213
	v_and_b32_e32 v201, 0xffff0000, v213
	v_max_f32_e32 v188, v188, v188
	v_max_f32_e32 v189, v189, v189
	v_max_f32_e32 v200, v200, v200
	v_max_f32_e32 v201, v201, v201
	v_max_f32_e32 v188, 0xda24260, v188
	v_max_f32_e32 v189, 0xda24260, v189
	v_max_f32_e32 v200, 0xda24260, v200
	v_max_f32_e32 v201, 0xda24260, v201
	v_rcp_f32_e32 v188, v188
	v_rcp_f32_e32 v189, v189
	v_rcp_f32_e32 v200, v200
	v_rcp_f32_e32 v201, v201
	v_lshlrev_b32_e32 v204, 16, v198
	v_and_b32_e32 v205, 0xffff0000, v198
	v_lshlrev_b32_e32 v214, 16, v199
	v_and_b32_e32 v215, 0xffff0000, v199
	v_pk_mul_f32 v[188:189], v[188:189], v[204:205]
	v_pk_mul_f32 v[200:201], v[200:201], v[214:215]
	v_pk_mul_f32 v[92:93], v[92:93], v[188:189]
	v_pk_mul_f32 v[94:95], v[94:95], v[200:201]
	s_waitcnt vmcnt(12)
;     __device__ __forceinline__ void hook(f32x4 (&acc)[2][2][4][2], const Unit& u, int wr, int wc, int fr, int fq) const {
;     ...
;         for (int g = 0; g < 8; ++g) { const int ai = g >> 2, m = g & 3, cb = g & 1, nb_ = cb ^ 1;
;             if (g < 7) { const int an = (g + 1) >> 2, mn = (g + 1) & 3;
; #pragma unroll
;                 for (int bj = 0; bj < 2; ++bj) { const bf16_t* gp = G + (size_t)(row0 + an * HALF + mn * 16) * ldg + col0 + bj * HALF; ga[nb_][bj] = *(const u32x4*)(gp + 6144); gb[nb_][bj] = *(const u32x4*)(gp + 8192); } }
; #pragma unroll
;             for (int bj = 0; bj < 2; ++bj) { f32x4 a0, a1, b0, b1; unpack_bf16x8(ga[cb][bj], a0, a1); unpack_bf16x8(gb[cb][bj], b0, b1);
; #pragma unroll
;                 for (int j = 0; j < 4; ++j) { a0[j] = a0[j] * __builtin_amdgcn_rcpf(fmaxf(b0[j], 1e-30f)); a1[j] = a1[j] * __builtin_amdgcn_rcpf(fmaxf(b1[j], 1e-30f)); }
;                 acc[ai][bj][m][0] = acc[ai][bj][m][0] * a0; acc[ai][bj][m][1] = acc[ai][bj][m][1] * a1; }
;             asm volatile("" ::: "memory"); }
	v_lshlrev_b32_e32 v188, 16, v228
	v_and_b32_e32 v189, 0xffff0000, v228
	v_lshlrev_b32_e32 v200, 16, v229
	v_and_b32_e32 v201, 0xffff0000, v229
	v_max_f32_e32 v188, v188, v188
	v_max_f32_e32 v189, v189, v189
	v_max_f32_e32 v200, v200, v200
	v_max_f32_e32 v201, v201, v201
	v_max_f32_e32 v188, 0xda24260, v188
	v_max_f32_e32 v189, 0xda24260, v189
	v_max_f32_e32 v200, 0xda24260, v200
	v_max_f32_e32 v201, 0xda24260, v201
	v_rcp_f32_e32 v188, v188
	v_rcp_f32_e32 v189, v189
	v_rcp_f32_e32 v200, v200
	v_rcp_f32_e32 v201, v201
	v_lshlrev_b32_e32 v204, 16, v224
	v_and_b32_e32 v205, 0xffff0000, v224
	v_lshlrev_b32_e32 v214, 16, v225
	v_and_b32_e32 v215, 0xffff0000, v225
	v_pk_mul_f32 v[188:189], v[188:189], v[204:205]
	v_pk_mul_f32 v[200:201], v[200:201], v[214:215]
	v_pk_mul_f32 v[88:89], v[88:89], v[188:189]
	v_pk_mul_f32 v[90:91], v[90:91], v[200:201]
	v_lshlrev_b32_e32 v188, 16, v230
	v_and_b32_e32 v189, 0xffff0000, v230
	v_lshlrev_b32_e32 v200, 16, v231
	v_and_b32_e32 v201, 0xffff0000, v231
	v_max_f32_e32 v188, v188, v188
	v_max_f32_e32 v189, v189, v189
	v_max_f32_e32 v200, v200, v200
	v_max_f32_e32 v201, v201, v201
	v_max_f32_e32 v188, 0xda24260, v188
	v_max_f32_e32 v189, 0xda24260, v189
	v_max_f32_e32 v200, 0xda24260, v200
	v_max_f32_e32 v201, 0xda24260, v201
	v_rcp_f32_e32 v188, v188
	v_rcp_f32_e32 v189, v189
	v_rcp_f32_e32 v200, v200
	v_rcp_f32_e32 v201, v201
	v_lshlrev_b32_e32 v204, 16, v226
	v_and_b32_e32 v205, 0xffff0000, v226
	v_lshlrev_b32_e32 v214, 16, v227
	v_and_b32_e32 v215, 0xffff0000, v227
	v_pk_mul_f32 v[188:189], v[188:189], v[204:205]
	v_pk_mul_f32 v[200:201], v[200:201], v[214:215]
	v_pk_mul_f32 v[84:85], v[84:85], v[188:189]
	v_pk_mul_f32 v[86:87], v[86:87], v[200:201]
	global_load_dwordx4 v[196:199], v2, s[98:99] nt
	global_load_dwordx4 v[210:213], v2, s[100:101]
	global_load_dwordx4 v[224:227], v2, s[98:99] offset:256 nt
	global_load_dwordx4 v[228:231], v2, s[100:101] offset:256
	v_add_u32_e32 v2, 0x50000, v2
	s_waitcnt vmcnt(14)
	v_lshlrev_b32_e32 v188, 16, v236
	v_and_b32_e32 v189, 0xffff0000, v236
	v_lshlrev_b32_e32 v200, 16, v237
	v_and_b32_e32 v201, 0xffff0000, v237
	v_max_f32_e32 v188, v188, v188
	v_max_f32_e32 v189, v189, v189
	v_max_f32_e32 v200, v200, v200
	v_max_f32_e32 v201, v201, v201
	v_max_f32_e32 v188, 0xda24260, v188
	v_max_f32_e32 v189, 0xda24260, v189
	v_max_f32_e32 v200, 0xda24260, v200
	v_max_f32_e32 v201, 0xda24260, v201
	v_rcp_f32_e32 v188, v188
	v_rcp_f32_e32 v189, v189
	v_rcp_f32_e32 v200, v200
	v_rcp_f32_e32 v201, v201
	v_lshlrev_b32_e32 v204, 16, v232
	v_and_b32_e32 v205, 0xffff0000, v232
	v_lshlrev_b32_e32 v214, 16, v233
	v_and_b32_e32 v215, 0xffff0000, v233
	v_pk_mul_f32 v[188:189], v[188:189], v[204:205]
	v_pk_mul_f32 v[200:201], v[200:201], v[214:215]
	v_pk_mul_f32 v[80:81], v[80:81], v[188:189]
	v_pk_mul_f32 v[82:83], v[82:83], v[200:201]
	v_lshlrev_b32_e32 v188, 16, v238
	v_and_b32_e32 v189, 0xffff0000, v238
	v_lshlrev_b32_e32 v200, 16, v239
	v_and_b32_e32 v201, 0xffff0000, v239
	v_max_f32_e32 v188, v188, v188
	v_max_f32_e32 v189, v189, v189
	v_max_f32_e32 v200, v200, v200
	v_max_f32_e32 v201, v201, v201
	v_max_f32_e32 v188, 0xda24260, v188
	v_max_f32_e32 v189, 0xda24260, v189
	v_max_f32_e32 v200, 0xda24260, v200
	v_max_f32_e32 v201, 0xda24260, v201
	v_rcp_f32_e32 v188, v188
	v_rcp_f32_e32 v189, v189
	v_rcp_f32_e32 v200, v200
	v_rcp_f32_e32 v201, v201
	v_lshlrev_b32_e32 v204, 16, v234
	v_and_b32_e32 v205, 0xffff0000, v234
	v_lshlrev_b32_e32 v214, 16, v235
	v_and_b32_e32 v215, 0xffff0000, v235
	v_pk_mul_f32 v[188:189], v[188:189], v[204:205]
	v_pk_mul_f32 v[200:201], v[200:201], v[214:215]
	v_pk_mul_f32 v[76:77], v[76:77], v[188:189]
	v_pk_mul_f32 v[78:79], v[78:79], v[200:201]
	s_waitcnt vmcnt(12)
	v_lshlrev_b32_e32 v188, 16, v244
	v_and_b32_e32 v189, 0xffff0000, v244
	v_lshlrev_b32_e32 v200, 16, v245
	v_and_b32_e32 v201, 0xffff0000, v245
	v_max_f32_e32 v188, v188, v188
	v_max_f32_e32 v189, v189, v189
	v_max_f32_e32 v200, v200, v200
	v_max_f32_e32 v201, v201, v201
	v_max_f32_e32 v188, 0xda24260, v188
	v_max_f32_e32 v189, 0xda24260, v189
	v_max_f32_e32 v200, 0xda24260, v200
	v_max_f32_e32 v201, 0xda24260, v201
	v_rcp_f32_e32 v188, v188
	v_rcp_f32_e32 v189, v189
	v_rcp_f32_e32 v200, v200
	v_rcp_f32_e32 v201, v201
	v_lshlrev_b32_e32 v204, 16, v240
	v_and_b32_e32 v205, 0xffff0000, v240
	v_lshlrev_b32_e32 v214, 16, v241
	v_and_b32_e32 v215, 0xffff0000, v241
	v_pk_mul_f32 v[188:189], v[188:189], v[204:205]
	v_pk_mul_f32 v[200:201], v[200:201], v[214:215]
	v_pk_mul_f32 v[72:73], v[72:73], v[188:189]
	v_pk_mul_f32 v[74:75], v[74:75], v[200:201]
	v_lshlrev_b32_e32 v188, 16, v246
	v_and_b32_e32 v189, 0xffff0000, v246
	v_lshlrev_b32_e32 v200, 16, v247
	v_and_b32_e32 v201, 0xffff0000, v247
	v_max_f32_e32 v188, v188, v188
	v_max_f32_e32 v189, v189, v189
	v_max_f32_e32 v200, v200, v200
	v_max_f32_e32 v201, v201, v201
	v_max_f32_e32 v188, 0xda24260, v188
	v_max_f32_e32 v189, 0xda24260, v189
	v_max_f32_e32 v200, 0xda24260, v200
	v_max_f32_e32 v201, 0xda24260, v201
	v_rcp_f32_e32 v188, v188
	v_rcp_f32_e32 v189, v189
	v_rcp_f32_e32 v200, v200
	v_rcp_f32_e32 v201, v201
	v_lshlrev_b32_e32 v204, 16, v242
	v_and_b32_e32 v205, 0xffff0000, v242
	v_lshlrev_b32_e32 v214, 16, v243
	v_and_b32_e32 v215, 0xffff0000, v243
	v_pk_mul_f32 v[188:189], v[188:189], v[204:205]
	v_pk_mul_f32 v[200:201], v[200:201], v[214:215]
	v_pk_mul_f32 v[68:69], v[68:69], v[188:189]
	v_pk_mul_f32 v[70:71], v[70:71], v[200:201]
	global_load_dwordx4 v[232:235], v2, s[98:99] nt
	global_load_dwordx4 v[236:239], v2, s[100:101]
	global_load_dwordx4 v[240:243], v2, s[98:99] offset:256 nt
	global_load_dwordx4 v[244:247], v2, s[100:101] offset:256
	s_waitcnt vmcnt(14)
;     __device__ __forceinline__ void hook(f32x4 (&acc)[2][2][4][2], const Unit& u, int wr, int wc, int fr, int fq) const {
;     ...
;         for (int g = 0; g < 8; ++g) { const int ai = g >> 2, m = g & 3, cb = g & 1, nb_ = cb ^ 1;
;             if (g < 7) { const int an = (g + 1) >> 2, mn = (g + 1) & 3;
; #pragma unroll
;                 for (int bj = 0; bj < 2; ++bj) { const bf16_t* gp = G + (size_t)(row0 + an * HALF + mn * 16) * ldg + col0 + bj * HALF; ga[nb_][bj] = *(const u32x4*)(gp + 6144); gb[nb_][bj] = *(const u32x4*)(gp + 8192); } }
; #pragma unroll
;             for (int bj = 0; bj < 2; ++bj) { f32x4 a0, a1, b0, b1; unpack_bf16x8(ga[cb][bj], a0, a1); unpack_bf16x8(gb[cb][bj], b0, b1);
; #pragma unroll
;                 for (int j = 0; j < 4; ++j) { a0[j] = a0[j] * __builtin_amdgcn_rcpf(fmaxf(b0[j], 1e-30f)); a1[j] = a1[j] * __builtin_amdgcn_rcpf(fmaxf(b1[j], 1e-30f)); }
;                 acc[ai][bj][m][0] = acc[ai][bj][m][0] * a0; acc[ai][bj][m][1] = acc[ai][bj][m][1] * a1; }
;             asm volatile("" ::: "memory"); }
	v_lshlrev_b32_e32 v188, 16, v136
	v_and_b32_e32 v189, 0xffff0000, v136
	v_lshlrev_b32_e32 v200, 16, v137
	v_and_b32_e32 v201, 0xffff0000, v137
	v_max_f32_e32 v188, v188, v188
	v_max_f32_e32 v189, v189, v189
	v_max_f32_e32 v200, v200, v200
	v_max_f32_e32 v201, v201, v201
	v_max_f32_e32 v188, 0xda24260, v188
	v_max_f32_e32 v189, 0xda24260, v189
	v_max_f32_e32 v200, 0xda24260, v200
	v_max_f32_e32 v201, 0xda24260, v201
	v_rcp_f32_e32 v188, v188
	v_rcp_f32_e32 v189, v189
	v_rcp_f32_e32 v200, v200
	v_rcp_f32_e32 v201, v201
	v_lshlrev_b32_e32 v204, 16, v132
	v_and_b32_e32 v205, 0xffff0000, v132
	v_lshlrev_b32_e32 v214, 16, v133
	v_and_b32_e32 v215, 0xffff0000, v133
	v_pk_mul_f32 v[188:189], v[188:189], v[204:205]
	v_pk_mul_f32 v[200:201], v[200:201], v[214:215]
	v_pk_mul_f32 v[64:65], v[64:65], v[188:189]
	v_pk_mul_f32 v[66:67], v[66:67], v[200:201]
	v_lshlrev_b32_e32 v188, 16, v138
	v_and_b32_e32 v189, 0xffff0000, v138
	v_lshlrev_b32_e32 v200, 16, v139
	v_and_b32_e32 v201, 0xffff0000, v139
	v_max_f32_e32 v188, v188, v188
	v_max_f32_e32 v189, v189, v189
	v_max_f32_e32 v200, v200, v200
	v_max_f32_e32 v201, v201, v201
	v_max_f32_e32 v188, 0xda24260, v188
	v_max_f32_e32 v189, 0xda24260, v189
	v_max_f32_e32 v200, 0xda24260, v200
	v_max_f32_e32 v201, 0xda24260, v201
	v_rcp_f32_e32 v188, v188
	v_rcp_f32_e32 v189, v189
	v_rcp_f32_e32 v200, v200
	v_rcp_f32_e32 v201, v201
	v_lshlrev_b32_e32 v204, 16, v134
	v_and_b32_e32 v205, 0xffff0000, v134
	v_lshlrev_b32_e32 v214, 16, v135
	v_and_b32_e32 v215, 0xffff0000, v135
	v_pk_mul_f32 v[188:189], v[188:189], v[204:205]
	v_pk_mul_f32 v[200:201], v[200:201], v[214:215]
	v_pk_mul_f32 v[60:61], v[60:61], v[188:189]
	v_pk_mul_f32 v[62:63], v[62:63], v[200:201]
	s_waitcnt vmcnt(12)
	v_lshlrev_b32_e32 v188, 16, v144
	v_and_b32_e32 v189, 0xffff0000, v144
	v_lshlrev_b32_e32 v200, 16, v145
	v_and_b32_e32 v201, 0xffff0000, v145
	v_max_f32_e32 v188, v188, v188
	v_max_f32_e32 v189, v189, v189
	v_max_f32_e32 v200, v200, v200
	v_max_f32_e32 v201, v201, v201
	v_max_f32_e32 v188, 0xda24260, v188
	v_max_f32_e32 v189, 0xda24260, v189
	v_max_f32_e32 v200, 0xda24260, v200
	v_max_f32_e32 v201, 0xda24260, v201
	v_rcp_f32_e32 v188, v188
	v_rcp_f32_e32 v189, v189
	v_rcp_f32_e32 v200, v200
	v_rcp_f32_e32 v201, v201
	v_lshlrev_b32_e32 v204, 16, v140
	v_and_b32_e32 v205, 0xffff0000, v140
	v_lshlrev_b32_e32 v214, 16, v141
	v_and_b32_e32 v215, 0xffff0000, v141
	v_pk_mul_f32 v[188:189], v[188:189], v[204:205]
	v_pk_mul_f32 v[200:201], v[200:201], v[214:215]
	v_pk_mul_f32 v[56:57], v[56:57], v[188:189]
	v_pk_mul_f32 v[58:59], v[58:59], v[200:201]
	v_lshlrev_b32_e32 v188, 16, v146
	v_and_b32_e32 v189, 0xffff0000, v146
	v_lshlrev_b32_e32 v200, 16, v147
	v_and_b32_e32 v201, 0xffff0000, v147
	v_max_f32_e32 v188, v188, v188
	v_max_f32_e32 v189, v189, v189
	v_max_f32_e32 v200, v200, v200
	v_max_f32_e32 v201, v201, v201
	v_max_f32_e32 v188, 0xda24260, v188
	v_max_f32_e32 v189, 0xda24260, v189
	v_max_f32_e32 v200, 0xda24260, v200
	v_max_f32_e32 v201, 0xda24260, v201
	v_rcp_f32_e32 v188, v188
	v_rcp_f32_e32 v189, v189
	v_rcp_f32_e32 v200, v200
	v_rcp_f32_e32 v201, v201
	v_lshlrev_b32_e32 v204, 16, v142
	v_and_b32_e32 v205, 0xffff0000, v142
	v_lshlrev_b32_e32 v214, 16, v143
	v_and_b32_e32 v215, 0xffff0000, v143
	v_pk_mul_f32 v[188:189], v[188:189], v[204:205]
	v_pk_mul_f32 v[200:201], v[200:201], v[214:215]
	v_pk_mul_f32 v[52:53], v[52:53], v[188:189]
	v_pk_mul_f32 v[54:55], v[54:55], v[200:201]
	s_waitcnt vmcnt(10)
	v_lshlrev_b32_e32 v188, 16, v152
	v_and_b32_e32 v189, 0xffff0000, v152
	v_lshlrev_b32_e32 v200, 16, v153
	v_and_b32_e32 v201, 0xffff0000, v153
	v_max_f32_e32 v188, v188, v188
	v_max_f32_e32 v189, v189, v189
	v_max_f32_e32 v200, v200, v200
	v_max_f32_e32 v201, v201, v201
	v_max_f32_e32 v188, 0xda24260, v188
	v_max_f32_e32 v189, 0xda24260, v189
	v_max_f32_e32 v200, 0xda24260, v200
	v_max_f32_e32 v201, 0xda24260, v201
	v_rcp_f32_e32 v188, v188
	v_rcp_f32_e32 v189, v189
	v_rcp_f32_e32 v200, v200
	v_rcp_f32_e32 v201, v201
	v_lshlrev_b32_e32 v204, 16, v148
	v_and_b32_e32 v205, 0xffff0000, v148
	v_lshlrev_b32_e32 v214, 16, v149
	v_and_b32_e32 v215, 0xffff0000, v149
	v_pk_mul_f32 v[188:189], v[188:189], v[204:205]
	v_pk_mul_f32 v[200:201], v[200:201], v[214:215]
	v_pk_mul_f32 v[48:49], v[48:49], v[188:189]
	v_pk_mul_f32 v[50:51], v[50:51], v[200:201]
	v_lshlrev_b32_e32 v188, 16, v154
	v_and_b32_e32 v189, 0xffff0000, v154
	v_lshlrev_b32_e32 v200, 16, v155
	v_and_b32_e32 v201, 0xffff0000, v155
	v_max_f32_e32 v188, v188, v188
	v_max_f32_e32 v189, v189, v189
	v_max_f32_e32 v200, v200, v200
	v_max_f32_e32 v201, v201, v201
	v_max_f32_e32 v188, 0xda24260, v188
	v_max_f32_e32 v189, 0xda24260, v189
	v_max_f32_e32 v200, 0xda24260, v200
	v_max_f32_e32 v201, 0xda24260, v201
	v_rcp_f32_e32 v188, v188
	v_rcp_f32_e32 v189, v189
	v_rcp_f32_e32 v200, v200
	v_rcp_f32_e32 v201, v201
	v_lshlrev_b32_e32 v204, 16, v150
	v_and_b32_e32 v205, 0xffff0000, v150
	v_lshlrev_b32_e32 v214, 16, v151
	v_and_b32_e32 v215, 0xffff0000, v151
	v_pk_mul_f32 v[188:189], v[188:189], v[204:205]
	v_pk_mul_f32 v[200:201], v[200:201], v[214:215]
	v_pk_mul_f32 v[44:45], v[44:45], v[188:189]
	v_pk_mul_f32 v[46:47], v[46:47], v[200:201]
	s_waitcnt vmcnt(8)
;     __device__ __forceinline__ void hook(f32x4 (&acc)[2][2][4][2], const Unit& u, int wr, int wc, int fr, int fq) const {
;     ...
;         for (int g = 0; g < 8; ++g) { const int ai = g >> 2, m = g & 3, cb = g & 1, nb_ = cb ^ 1;
;             if (g < 7) { const int an = (g + 1) >> 2, mn = (g + 1) & 3;
; #pragma unroll
;                 for (int bj = 0; bj < 2; ++bj) { const bf16_t* gp = G + (size_t)(row0 + an * HALF + mn * 16) * ldg + col0 + bj * HALF; ga[nb_][bj] = *(const u32x4*)(gp + 6144); gb[nb_][bj] = *(const u32x4*)(gp + 8192); } }
; #pragma unroll
;             for (int bj = 0; bj < 2; ++bj) { f32x4 a0, a1, b0, b1; unpack_bf16x8(ga[cb][bj], a0, a1); unpack_bf16x8(gb[cb][bj], b0, b1);
; #pragma unroll
;                 for (int j = 0; j < 4; ++j) { a0[j] = a0[j] * __builtin_amdgcn_rcpf(fmaxf(b0[j], 1e-30f)); a1[j] = a1[j] * __builtin_amdgcn_rcpf(fmaxf(b1[j], 1e-30f)); }
;                 acc[ai][bj][m][0] = acc[ai][bj][m][0] * a0; acc[ai][bj][m][1] = acc[ai][bj][m][1] * a1; }
;             asm volatile("" ::: "memory"); }
	v_lshlrev_b32_e32 v188, 16, v160
	v_and_b32_e32 v189, 0xffff0000, v160
	v_lshlrev_b32_e32 v200, 16, v161
	v_and_b32_e32 v201, 0xffff0000, v161
	v_max_f32_e32 v188, v188, v188
	v_max_f32_e32 v189, v189, v189
	v_max_f32_e32 v200, v200, v200
	v_max_f32_e32 v201, v201, v201
	v_max_f32_e32 v188, 0xda24260, v188
	v_max_f32_e32 v189, 0xda24260, v189
	v_max_f32_e32 v200, 0xda24260, v200
	v_max_f32_e32 v201, 0xda24260, v201
	v_rcp_f32_e32 v188, v188
	v_rcp_f32_e32 v189, v189
	v_rcp_f32_e32 v200, v200
	v_rcp_f32_e32 v201, v201
	v_lshlrev_b32_e32 v204, 16, v156
	v_and_b32_e32 v205, 0xffff0000, v156
	v_lshlrev_b32_e32 v214, 16, v157
	v_and_b32_e32 v215, 0xffff0000, v157
	v_pk_mul_f32 v[188:189], v[188:189], v[204:205]
	v_pk_mul_f32 v[200:201], v[200:201], v[214:215]
	v_pk_mul_f32 v[40:41], v[40:41], v[188:189]
	v_pk_mul_f32 v[42:43], v[42:43], v[200:201]
	v_lshlrev_b32_e32 v188, 16, v162
	v_and_b32_e32 v189, 0xffff0000, v162
	v_lshlrev_b32_e32 v200, 16, v163
	v_and_b32_e32 v201, 0xffff0000, v163
	v_max_f32_e32 v188, v188, v188
	v_max_f32_e32 v189, v189, v189
	v_max_f32_e32 v200, v200, v200
	v_max_f32_e32 v201, v201, v201
	v_max_f32_e32 v188, 0xda24260, v188
	v_max_f32_e32 v189, 0xda24260, v189
	v_max_f32_e32 v200, 0xda24260, v200
	v_max_f32_e32 v201, 0xda24260, v201
	v_rcp_f32_e32 v188, v188
	v_rcp_f32_e32 v189, v189
	v_rcp_f32_e32 v200, v200
	v_rcp_f32_e32 v201, v201
	v_lshlrev_b32_e32 v204, 16, v158
	v_and_b32_e32 v205, 0xffff0000, v158
	v_lshlrev_b32_e32 v214, 16, v159
	v_and_b32_e32 v215, 0xffff0000, v159
	v_pk_mul_f32 v[188:189], v[188:189], v[204:205]
	v_pk_mul_f32 v[200:201], v[200:201], v[214:215]
	v_pk_mul_f32 v[36:37], v[36:37], v[188:189]
	v_pk_mul_f32 v[38:39], v[38:39], v[200:201]
	s_waitcnt vmcnt(6)
	v_lshlrev_b32_e32 v188, 16, v210
	v_and_b32_e32 v189, 0xffff0000, v210
	v_lshlrev_b32_e32 v200, 16, v211
	v_and_b32_e32 v201, 0xffff0000, v211
	v_max_f32_e32 v188, v188, v188
	v_max_f32_e32 v189, v189, v189
	v_max_f32_e32 v200, v200, v200
	v_max_f32_e32 v201, v201, v201
	v_max_f32_e32 v188, 0xda24260, v188
	v_max_f32_e32 v189, 0xda24260, v189
	v_max_f32_e32 v200, 0xda24260, v200
	v_max_f32_e32 v201, 0xda24260, v201
	v_rcp_f32_e32 v188, v188
	v_rcp_f32_e32 v189, v189
	v_rcp_f32_e32 v200, v200
	v_rcp_f32_e32 v201, v201
	v_lshlrev_b32_e32 v204, 16, v196
	v_and_b32_e32 v205, 0xffff0000, v196
	v_lshlrev_b32_e32 v214, 16, v197
	v_and_b32_e32 v215, 0xffff0000, v197
	v_pk_mul_f32 v[188:189], v[188:189], v[204:205]
	v_pk_mul_f32 v[200:201], v[200:201], v[214:215]
	v_pk_mul_f32 v[32:33], v[32:33], v[188:189]
	v_pk_mul_f32 v[34:35], v[34:35], v[200:201]
	v_lshlrev_b32_e32 v188, 16, v212
	v_and_b32_e32 v189, 0xffff0000, v212
	v_lshlrev_b32_e32 v200, 16, v213
	v_and_b32_e32 v201, 0xffff0000, v213
	v_max_f32_e32 v188, v188, v188
	v_max_f32_e32 v189, v189, v189
	v_max_f32_e32 v200, v200, v200
	v_max_f32_e32 v201, v201, v201
	v_max_f32_e32 v188, 0xda24260, v188
	v_max_f32_e32 v189, 0xda24260, v189
	v_max_f32_e32 v200, 0xda24260, v200
	v_max_f32_e32 v201, 0xda24260, v201
	v_rcp_f32_e32 v188, v188
	v_rcp_f32_e32 v189, v189
	v_rcp_f32_e32 v200, v200
	v_rcp_f32_e32 v201, v201
	v_lshlrev_b32_e32 v204, 16, v198
	v_and_b32_e32 v205, 0xffff0000, v198
	v_lshlrev_b32_e32 v214, 16, v199
	v_and_b32_e32 v215, 0xffff0000, v199
	v_pk_mul_f32 v[188:189], v[188:189], v[204:205]
	v_pk_mul_f32 v[200:201], v[200:201], v[214:215]
	v_pk_mul_f32 v[28:29], v[28:29], v[188:189]
	v_pk_mul_f32 v[30:31], v[30:31], v[200:201]
	s_waitcnt vmcnt(4)
;     __device__ __forceinline__ void hook(f32x4 (&acc)[2][2][4][2], const Unit& u, int wr, int wc, int fr, int fq) const {
;     ...
;         for (int g = 0; g < 8; ++g) { const int ai = g >> 2, m = g & 3, cb = g & 1, nb_ = cb ^ 1;
;             if (g < 7) { const int an = (g + 1) >> 2, mn = (g + 1) & 3;
; #pragma unroll
;                 for (int bj = 0; bj < 2; ++bj) { const bf16_t* gp = G + (size_t)(row0 + an * HALF + mn * 16) * ldg + col0 + bj * HALF; ga[nb_][bj] = *(const u32x4*)(gp + 6144); gb[nb_][bj] = *(const u32x4*)(gp + 8192); } }
; #pragma unroll
;             for (int bj = 0; bj < 2; ++bj) { f32x4 a0, a1, b0, b1; unpack_bf16x8(ga[cb][bj], a0, a1); unpack_bf16x8(gb[cb][bj], b0, b1);
; #pragma unroll
;                 for (int j = 0; j < 4; ++j) { a0[j] = a0[j] * __builtin_amdgcn_rcpf(fmaxf(b0[j], 1e-30f)); a1[j] = a1[j] * __builtin_amdgcn_rcpf(fmaxf(b1[j], 1e-30f)); }
;                 acc[ai][bj][m][0] = acc[ai][bj][m][0] * a0; acc[ai][bj][m][1] = acc[ai][bj][m][1] * a1; }
;             asm volatile("" ::: "memory"); }
	v_lshlrev_b32_e32 v188, 16, v228
	v_and_b32_e32 v189, 0xffff0000, v228
	v_lshlrev_b32_e32 v200, 16, v229
	v_and_b32_e32 v201, 0xffff0000, v229
	v_max_f32_e32 v188, v188, v188
	v_max_f32_e32 v189, v189, v189
	v_max_f32_e32 v200, v200, v200
	v_max_f32_e32 v201, v201, v201
	v_max_f32_e32 v188, 0xda24260, v188
	v_max_f32_e32 v189, 0xda24260, v189
	v_max_f32_e32 v200, 0xda24260, v200
	v_max_f32_e32 v201, 0xda24260, v201
	v_rcp_f32_e32 v188, v188
	v_rcp_f32_e32 v189, v189
	v_rcp_f32_e32 v200, v200
	v_rcp_f32_e32 v201, v201
	v_lshlrev_b32_e32 v204, 16, v224
	v_and_b32_e32 v205, 0xffff0000, v224
	v_lshlrev_b32_e32 v214, 16, v225
	v_and_b32_e32 v215, 0xffff0000, v225
	v_pk_mul_f32 v[188:189], v[188:189], v[204:205]
	v_pk_mul_f32 v[200:201], v[200:201], v[214:215]
	v_pk_mul_f32 v[24:25], v[24:25], v[188:189]
	v_pk_mul_f32 v[26:27], v[26:27], v[200:201]
	v_lshlrev_b32_e32 v188, 16, v230
	v_and_b32_e32 v189, 0xffff0000, v230
	v_lshlrev_b32_e32 v200, 16, v231
	v_and_b32_e32 v201, 0xffff0000, v231
	v_max_f32_e32 v188, v188, v188
	v_max_f32_e32 v189, v189, v189
	v_max_f32_e32 v200, v200, v200
	v_max_f32_e32 v201, v201, v201
	v_max_f32_e32 v188, 0xda24260, v188
	v_max_f32_e32 v189, 0xda24260, v189
	v_max_f32_e32 v200, 0xda24260, v200
	v_max_f32_e32 v201, 0xda24260, v201
	v_rcp_f32_e32 v188, v188
	v_rcp_f32_e32 v189, v189
	v_rcp_f32_e32 v200, v200
	v_rcp_f32_e32 v201, v201
	v_lshlrev_b32_e32 v204, 16, v226
	v_and_b32_e32 v205, 0xffff0000, v226
	v_lshlrev_b32_e32 v214, 16, v227
	v_and_b32_e32 v215, 0xffff0000, v227
	v_pk_mul_f32 v[188:189], v[188:189], v[204:205]
	v_pk_mul_f32 v[200:201], v[200:201], v[214:215]
	v_pk_mul_f32 v[20:21], v[20:21], v[188:189]
	v_pk_mul_f32 v[22:23], v[22:23], v[200:201]
	s_waitcnt vmcnt(2)
	v_lshlrev_b32_e32 v188, 16, v236
	v_and_b32_e32 v189, 0xffff0000, v236
	v_lshlrev_b32_e32 v200, 16, v237
	v_and_b32_e32 v201, 0xffff0000, v237
	v_max_f32_e32 v188, v188, v188
	v_max_f32_e32 v189, v189, v189
	v_max_f32_e32 v200, v200, v200
	v_max_f32_e32 v201, v201, v201
	v_max_f32_e32 v188, 0xda24260, v188
	v_max_f32_e32 v189, 0xda24260, v189
	v_max_f32_e32 v200, 0xda24260, v200
	v_max_f32_e32 v201, 0xda24260, v201
	v_rcp_f32_e32 v188, v188
	v_rcp_f32_e32 v189, v189
	v_rcp_f32_e32 v200, v200
	v_rcp_f32_e32 v201, v201
	v_lshlrev_b32_e32 v204, 16, v232
	v_and_b32_e32 v205, 0xffff0000, v232
	v_lshlrev_b32_e32 v214, 16, v233
	v_and_b32_e32 v215, 0xffff0000, v233
	v_pk_mul_f32 v[188:189], v[188:189], v[204:205]
	v_pk_mul_f32 v[200:201], v[200:201], v[214:215]
	v_pk_mul_f32 v[16:17], v[16:17], v[188:189]
	v_pk_mul_f32 v[18:19], v[18:19], v[200:201]
	v_lshlrev_b32_e32 v188, 16, v238
	v_and_b32_e32 v189, 0xffff0000, v238
	v_lshlrev_b32_e32 v200, 16, v239
	v_and_b32_e32 v201, 0xffff0000, v239
	v_max_f32_e32 v188, v188, v188
	v_max_f32_e32 v189, v189, v189
	v_max_f32_e32 v200, v200, v200
	v_max_f32_e32 v201, v201, v201
	v_max_f32_e32 v188, 0xda24260, v188
	v_max_f32_e32 v189, 0xda24260, v189
	v_max_f32_e32 v200, 0xda24260, v200
	v_max_f32_e32 v201, 0xda24260, v201
	v_rcp_f32_e32 v188, v188
	v_rcp_f32_e32 v189, v189
	v_rcp_f32_e32 v200, v200
	v_rcp_f32_e32 v201, v201
	v_lshlrev_b32_e32 v204, 16, v234
	v_and_b32_e32 v205, 0xffff0000, v234
	v_lshlrev_b32_e32 v214, 16, v235
	v_and_b32_e32 v215, 0xffff0000, v235
	v_pk_mul_f32 v[188:189], v[188:189], v[204:205]
	v_pk_mul_f32 v[200:201], v[200:201], v[214:215]
	v_pk_mul_f32 v[12:13], v[12:13], v[188:189]
	v_pk_mul_f32 v[14:15], v[14:15], v[200:201]
	s_waitcnt vmcnt(0)
	v_lshlrev_b32_e32 v188, 16, v244
	v_and_b32_e32 v189, 0xffff0000, v244
	v_lshlrev_b32_e32 v200, 16, v245
	v_and_b32_e32 v201, 0xffff0000, v245
	v_max_f32_e32 v188, v188, v188
	v_max_f32_e32 v189, v189, v189
	v_max_f32_e32 v200, v200, v200
	v_max_f32_e32 v201, v201, v201
	v_max_f32_e32 v188, 0xda24260, v188
	v_max_f32_e32 v189, 0xda24260, v189
	v_max_f32_e32 v200, 0xda24260, v200
	v_max_f32_e32 v201, 0xda24260, v201
	v_rcp_f32_e32 v188, v188
	v_rcp_f32_e32 v189, v189
	v_rcp_f32_e32 v200, v200
	v_rcp_f32_e32 v201, v201
	v_lshlrev_b32_e32 v204, 16, v240
	v_and_b32_e32 v205, 0xffff0000, v240
	v_lshlrev_b32_e32 v214, 16, v241
	v_and_b32_e32 v215, 0xffff0000, v241
	v_pk_mul_f32 v[188:189], v[188:189], v[204:205]
	v_pk_mul_f32 v[200:201], v[200:201], v[214:215]
	v_pk_mul_f32 v[8:9], v[8:9], v[188:189]
	v_pk_mul_f32 v[10:11], v[10:11], v[200:201]
	v_lshlrev_b32_e32 v188, 16, v246
	v_and_b32_e32 v189, 0xffff0000, v246
	v_lshlrev_b32_e32 v200, 16, v247
	v_and_b32_e32 v201, 0xffff0000, v247
	v_max_f32_e32 v188, v188, v188
	v_max_f32_e32 v189, v189, v189
	v_max_f32_e32 v200, v200, v200
	v_max_f32_e32 v201, v201, v201
	v_max_f32_e32 v188, 0xda24260, v188
	v_max_f32_e32 v189, 0xda24260, v189
	v_max_f32_e32 v200, 0xda24260, v200
	v_max_f32_e32 v201, 0xda24260, v201
	v_rcp_f32_e32 v188, v188
	v_rcp_f32_e32 v189, v189
	v_rcp_f32_e32 v200, v200
	v_rcp_f32_e32 v201, v201
	v_lshlrev_b32_e32 v204, 16, v242
	v_and_b32_e32 v205, 0xffff0000, v242
	v_lshlrev_b32_e32 v214, 16, v243
	v_and_b32_e32 v215, 0xffff0000, v243
	v_pk_mul_f32 v[188:189], v[188:189], v[204:205]
	v_pk_mul_f32 v[200:201], v[200:201], v[214:215]
	v_pk_mul_f32 v[4:5], v[4:5], v[188:189]
	v_pk_mul_f32 v[6:7], v[6:7], v[200:201]
	s_branch .LBB0_754

; __device__ __forceinline__ unsigned cvt_pk_bf16(float lo, float hi) { unsigned r; asm volatile("v_cvt_pk_bf16_f32 %0, %1, %2" : "=v"(r) : "v"(lo), "v"(hi)); return r; }
;     __device__ __forceinline__ void operator()(const f32x4 (&acc)[2][2][4][2], const Unit& u, int wr, int wc, int fr, int fq) const {
;     ...
;         u32x4 gb[2][2];
; #pragma unroll
;         for (int bj = 0; bj < 2; ++bj) gb[0][bj] = *(const u32x4*)(G + (size_t)row0 * ldg + 8192 + col0 + bj * HALF);
; #pragma unroll
;         for (int g = 0; g < 8; ++g) { const int ai = g >> 2, m = g & 3, cb = g & 1, nb_ = cb ^ 1; const size_t row = (size_t)(row0 + ai * HALF + m * 16);
;             if (g < 7) { const int an = (g + 1) >> 2, mn = (g + 1) & 3;
; #pragma unroll
;                 for (int bj = 0; bj < 2; ++bj) gb[nb_][bj] = *(const u32x4*)(G + (size_t)(row0 + an * HALF + mn * 16) * ldg + 8192 + col0 + bj * HALF); }
; #pragma unroll
;             for (int bj = 0; bj < 2; ++bj) { f32x4 b0, b1; unpack_bf16x8(gb[cb][bj], b0, b1);
; #pragma unroll
;                 for (int j = 0; j < 4; ++j) { b0[j] = fmaxf(b0[j], 1e-30f); b1[j] = fmaxf(b1[j], 1e-30f); }
;                 const f32x4 v0 = acc[ai][bj][m][0] * b0, v1 = acc[ai][bj][m][1] * b1;
;                 u32x4 w; w.x = cvt_pk_bf16(v0[0], v0[1]); w.y = cvt_pk_bf16(v0[2], v0[3]); w.z = cvt_pk_bf16(v1[0], v1[1]); w.w = cvt_pk_bf16(v1[2], v1[3]);
;                 *(u32x4*)(O + row * 2048 + col0 + bj * HALF) = w; }
;             asm volatile("" ::: "memory"); }
.LBB0_763:
	v_mov_b64_e32 v[188:189], s[8:9]
	v_mad_i64_i32 v[2:3], s[20:21], v180, s25, v[188:189]
	v_lshlrev_b64 v[188:189], 1, v[182:183]
	v_lshl_add_u64 v[214:215], v[144:145], 0, v[188:189]
	v_lshl_add_u64 v[2:3], v[2:3], 0, v[188:189]
	s_mov_b64 s[44:45], 0x4000
	s_mov_b64 s[98:99], 0x50000
	s_mov_b64 s[100:101], 0x190000
	s_mov_b64 s[20:21], 0x10000
	v_lshl_add_u64 v[2:3], v[2:3], 0, s[44:45]
	global_load_dwordx4 v[132:135], v[2:3], off
	global_load_dwordx4 v[136:139], v[2:3], off offset:256
	v_lshl_add_u64 v[188:189], v[2:3], 0, s[98:99]
	global_load_dwordx4 v[140:143], v[188:189], off
	global_load_dwordx4 v[144:147], v[188:189], off offset:256
	v_lshl_add_u64 v[2:3], v[188:189], 0, s[98:99]
	global_load_dwordx4 v[148:151], v[2:3], off
	global_load_dwordx4 v[152:155], v[2:3], off offset:256
	v_lshl_add_u64 v[188:189], v[2:3], 0, s[98:99]
	global_load_dwordx4 v[156:159], v[188:189], off
	global_load_dwordx4 v[160:163], v[188:189], off offset:256
	v_lshl_add_u64 v[2:3], v[188:189], 0, s[100:101]
	global_load_dwordx4 v[196:199], v[2:3], off
	global_load_dwordx4 v[210:213], v[2:3], off offset:256
	v_lshl_add_u64 v[188:189], v[2:3], 0, s[98:99]
	global_load_dwordx4 v[224:227], v[188:189], off
	global_load_dwordx4 v[228:231], v[188:189], off offset:256
	v_lshl_add_u64 v[2:3], v[188:189], 0, s[98:99]
	global_load_dwordx4 v[232:235], v[2:3], off
	global_load_dwordx4 v[236:239], v[2:3], off offset:256
	v_lshl_add_u64 v[188:189], v[2:3], 0, s[98:99]
	global_load_dwordx4 v[240:243], v[188:189], off
	global_load_dwordx4 v[244:247], v[188:189], off offset:256
	s_waitcnt vmcnt(15)
	v_lshlrev_b32_e32 v184, 16, v132
	v_and_b32_e32 v185, 0xffff0000, v132
	v_lshlrev_b32_e32 v186, 16, v133
	v_and_b32_e32 v187, 0xffff0000, v133
	v_lshlrev_b32_e32 v200, 16, v134
	v_and_b32_e32 v201, 0xffff0000, v134
	v_lshlrev_b32_e32 v204, 16, v135
	v_and_b32_e32 v205, 0xffff0000, v135
	v_max_f32_e32 v184, v184, v184
	v_max_f32_e32 v185, v185, v185
	v_max_f32_e32 v186, v186, v186
	v_max_f32_e32 v187, v187, v187
	v_max_f32_e32 v200, v200, v200
	v_max_f32_e32 v201, v201, v201
	v_max_f32_e32 v204, v204, v204
	v_max_f32_e32 v205, v205, v205
	v_max_f32_e32 v184, 0xda24260, v184
	v_max_f32_e32 v185, 0xda24260, v185
	v_max_f32_e32 v186, 0xda24260, v186
	v_max_f32_e32 v187, 0xda24260, v187
	v_max_f32_e32 v200, 0xda24260, v200
	v_max_f32_e32 v201, 0xda24260, v201
	v_max_f32_e32 v204, 0xda24260, v204
	v_max_f32_e32 v205, 0xda24260, v205
	v_pk_mul_f32 v[120:121], v[120:121], v[184:185]
	v_pk_mul_f32 v[122:123], v[122:123], v[186:187]
	v_pk_mul_f32 v[116:117], v[116:117], v[200:201]
	v_pk_mul_f32 v[118:119], v[118:119], v[204:205]
	v_cvt_pk_bf16_f32 v132, v120, v121
	v_cvt_pk_bf16_f32 v133, v122, v123
	v_cvt_pk_bf16_f32 v134, v116, v117
	v_cvt_pk_bf16_f32 v135, v118, v119
	global_store_dwordx4 v[214:215], v[132:135], off
	s_waitcnt vmcnt(15)
	v_lshlrev_b32_e32 v184, 16, v136
	v_and_b32_e32 v185, 0xffff0000, v136
	v_lshlrev_b32_e32 v186, 16, v137
	v_and_b32_e32 v187, 0xffff0000, v137
	v_lshlrev_b32_e32 v200, 16, v138
	v_and_b32_e32 v201, 0xffff0000, v138
	v_lshlrev_b32_e32 v204, 16, v139
	v_and_b32_e32 v205, 0xffff0000, v139
	v_max_f32_e32 v184, v184, v184
	v_max_f32_e32 v185, v185, v185
	v_max_f32_e32 v186, v186, v186
	v_max_f32_e32 v187, v187, v187
	v_max_f32_e32 v200, v200, v200
	v_max_f32_e32 v201, v201, v201
	v_max_f32_e32 v204, v204, v204
	v_max_f32_e32 v205, v205, v205
	v_max_f32_e32 v184, 0xda24260, v184
	v_max_f32_e32 v185, 0xda24260, v185
	v_max_f32_e32 v186, 0xda24260, v186
	v_max_f32_e32 v187, 0xda24260, v187
	v_max_f32_e32 v200, 0xda24260, v200
	v_max_f32_e32 v201, 0xda24260, v201
	v_max_f32_e32 v204, 0xda24260, v204
	v_max_f32_e32 v205, 0xda24260, v205
	v_pk_mul_f32 v[128:129], v[128:129], v[184:185]
	v_pk_mul_f32 v[130:131], v[130:131], v[186:187]
	v_pk_mul_f32 v[124:125], v[124:125], v[200:201]
	v_pk_mul_f32 v[126:127], v[126:127], v[204:205]
	v_cvt_pk_bf16_f32 v136, v128, v129
	v_cvt_pk_bf16_f32 v137, v130, v131
	v_cvt_pk_bf16_f32 v138, v124, v125
	v_cvt_pk_bf16_f32 v139, v126, v127
	global_store_dwordx4 v[214:215], v[136:139], off offset:256
	v_lshl_add_u64 v[180:181], v[214:215], 0, s[20:21]
	s_waitcnt vmcnt(15)
	v_lshlrev_b32_e32 v184, 16, v140
	v_and_b32_e32 v185, 0xffff0000, v140
	v_lshlrev_b32_e32 v186, 16, v141
	v_and_b32_e32 v187, 0xffff0000, v141
	v_lshlrev_b32_e32 v200, 16, v142
	v_and_b32_e32 v201, 0xffff0000, v142
	v_lshlrev_b32_e32 v204, 16, v143
	v_and_b32_e32 v205, 0xffff0000, v143
	v_max_f32_e32 v184, v184, v184
	v_max_f32_e32 v185, v185, v185
	v_max_f32_e32 v186, v186, v186
	v_max_f32_e32 v187, v187, v187
	v_max_f32_e32 v200, v200, v200
	v_max_f32_e32 v201, v201, v201
	v_max_f32_e32 v204, v204, v204
	v_max_f32_e32 v205, v205, v205
	v_max_f32_e32 v184, 0xda24260, v184
	v_max_f32_e32 v185, 0xda24260, v185
	v_max_f32_e32 v186, 0xda24260, v186
	v_max_f32_e32 v187, 0xda24260, v187
	v_max_f32_e32 v200, 0xda24260, v200
	v_max_f32_e32 v201, 0xda24260, v201
	v_max_f32_e32 v204, 0xda24260, v204
	v_max_f32_e32 v205, 0xda24260, v205
	v_pk_mul_f32 v[112:113], v[112:113], v[184:185]
	v_pk_mul_f32 v[114:115], v[114:115], v[186:187]
	v_pk_mul_f32 v[108:109], v[108:109], v[200:201]
	v_pk_mul_f32 v[110:111], v[110:111], v[204:205]
	v_cvt_pk_bf16_f32 v140, v112, v113
	v_cvt_pk_bf16_f32 v141, v114, v115
	v_cvt_pk_bf16_f32 v142, v108, v109
	v_cvt_pk_bf16_f32 v143, v110, v111
	global_store_dwordx4 v[180:181], v[140:143], off
	s_waitcnt vmcnt(15)
; __device__ __forceinline__ unsigned cvt_pk_bf16(float lo, float hi) { unsigned r; asm volatile("v_cvt_pk_bf16_f32 %0, %1, %2" : "=v"(r) : "v"(lo), "v"(hi)); return r; }
;     __device__ __forceinline__ void operator()(const f32x4 (&acc)[2][2][4][2], const Unit& u, int wr, int wc, int fr, int fq) const {
;     ...
;             for (int bj = 0; bj < 2; ++bj) { f32x4 b0, b1; unpack_bf16x8(gb[cb][bj], b0, b1);
; #pragma unroll
;                 for (int j = 0; j < 4; ++j) { b0[j] = fmaxf(b0[j], 1e-30f); b1[j] = fmaxf(b1[j], 1e-30f); }
;                 const f32x4 v0 = acc[ai][bj][m][0] * b0, v1 = acc[ai][bj][m][1] * b1;
;                 u32x4 w; w.x = cvt_pk_bf16(v0[0], v0[1]); w.y = cvt_pk_bf16(v0[2], v0[3]); w.z = cvt_pk_bf16(v1[0], v1[1]); w.w = cvt_pk_bf16(v1[2], v1[3]);
;                 *(u32x4*)(O + row * 2048 + col0 + bj * HALF) = w; }
;             asm volatile("" ::: "memory"); }
	v_lshlrev_b32_e32 v184, 16, v144
	v_and_b32_e32 v185, 0xffff0000, v144
	v_lshlrev_b32_e32 v186, 16, v145
	v_and_b32_e32 v187, 0xffff0000, v145
	v_lshlrev_b32_e32 v200, 16, v146
	v_and_b32_e32 v201, 0xffff0000, v146
	v_lshlrev_b32_e32 v204, 16, v147
	v_and_b32_e32 v205, 0xffff0000, v147
	v_max_f32_e32 v184, v184, v184
	v_max_f32_e32 v185, v185, v185
	v_max_f32_e32 v186, v186, v186
	v_max_f32_e32 v187, v187, v187
	v_max_f32_e32 v200, v200, v200
	v_max_f32_e32 v201, v201, v201
	v_max_f32_e32 v204, v204, v204
	v_max_f32_e32 v205, v205, v205
	v_max_f32_e32 v184, 0xda24260, v184
	v_max_f32_e32 v185, 0xda24260, v185
	v_max_f32_e32 v186, 0xda24260, v186
	v_max_f32_e32 v187, 0xda24260, v187
	v_max_f32_e32 v200, 0xda24260, v200
	v_max_f32_e32 v201, 0xda24260, v201
	v_max_f32_e32 v204, 0xda24260, v204
	v_max_f32_e32 v205, 0xda24260, v205
	v_pk_mul_f32 v[104:105], v[104:105], v[184:185]
	v_pk_mul_f32 v[106:107], v[106:107], v[186:187]
	v_pk_mul_f32 v[100:101], v[100:101], v[200:201]
	v_pk_mul_f32 v[102:103], v[102:103], v[204:205]
	v_cvt_pk_bf16_f32 v144, v104, v105
	v_cvt_pk_bf16_f32 v145, v106, v107
	v_cvt_pk_bf16_f32 v146, v100, v101
	v_cvt_pk_bf16_f32 v147, v102, v103
	global_store_dwordx4 v[180:181], v[144:147], off offset:256
	v_lshl_add_u64 v[214:215], v[180:181], 0, s[20:21]
	s_waitcnt vmcnt(15)
	v_lshlrev_b32_e32 v184, 16, v148
	v_and_b32_e32 v185, 0xffff0000, v148
	v_lshlrev_b32_e32 v186, 16, v149
	v_and_b32_e32 v187, 0xffff0000, v149
	v_lshlrev_b32_e32 v200, 16, v150
	v_and_b32_e32 v201, 0xffff0000, v150
	v_lshlrev_b32_e32 v204, 16, v151
	v_and_b32_e32 v205, 0xffff0000, v151
	v_max_f32_e32 v184, v184, v184
	v_max_f32_e32 v185, v185, v185
	v_max_f32_e32 v186, v186, v186
	v_max_f32_e32 v187, v187, v187
	v_max_f32_e32 v200, v200, v200
	v_max_f32_e32 v201, v201, v201
	v_max_f32_e32 v204, v204, v204
	v_max_f32_e32 v205, v205, v205
	v_max_f32_e32 v184, 0xda24260, v184
	v_max_f32_e32 v185, 0xda24260, v185
	v_max_f32_e32 v186, 0xda24260, v186
	v_max_f32_e32 v187, 0xda24260, v187
	v_max_f32_e32 v200, 0xda24260, v200
	v_max_f32_e32 v201, 0xda24260, v201
	v_max_f32_e32 v204, 0xda24260, v204
	v_max_f32_e32 v205, 0xda24260, v205
	v_pk_mul_f32 v[96:97], v[96:97], v[184:185]
	v_pk_mul_f32 v[98:99], v[98:99], v[186:187]
	v_pk_mul_f32 v[92:93], v[92:93], v[200:201]
	v_pk_mul_f32 v[94:95], v[94:95], v[204:205]
	v_cvt_pk_bf16_f32 v148, v96, v97
	v_cvt_pk_bf16_f32 v149, v98, v99
	v_cvt_pk_bf16_f32 v150, v92, v93
	v_cvt_pk_bf16_f32 v151, v94, v95
	global_store_dwordx4 v[214:215], v[148:151], off
	s_waitcnt vmcnt(15)
	v_lshlrev_b32_e32 v184, 16, v152
	v_and_b32_e32 v185, 0xffff0000, v152
	v_lshlrev_b32_e32 v186, 16, v153
	v_and_b32_e32 v187, 0xffff0000, v153
	v_lshlrev_b32_e32 v200, 16, v154
	v_and_b32_e32 v201, 0xffff0000, v154
	v_lshlrev_b32_e32 v204, 16, v155
	v_and_b32_e32 v205, 0xffff0000, v155
	v_max_f32_e32 v184, v184, v184
	v_max_f32_e32 v185, v185, v185
	v_max_f32_e32 v186, v186, v186
	v_max_f32_e32 v187, v187, v187
	v_max_f32_e32 v200, v200, v200
	v_max_f32_e32 v201, v201, v201
	v_max_f32_e32 v204, v204, v204
	v_max_f32_e32 v205, v205, v205
	v_max_f32_e32 v184, 0xda24260, v184
	v_max_f32_e32 v185, 0xda24260, v185
	v_max_f32_e32 v186, 0xda24260, v186
	v_max_f32_e32 v187, 0xda24260, v187
	v_max_f32_e32 v200, 0xda24260, v200
	v_max_f32_e32 v201, 0xda24260, v201
	v_max_f32_e32 v204, 0xda24260, v204
	v_max_f32_e32 v205, 0xda24260, v205
	v_pk_mul_f32 v[88:89], v[88:89], v[184:185]
	v_pk_mul_f32 v[90:91], v[90:91], v[186:187]
	v_pk_mul_f32 v[84:85], v[84:85], v[200:201]
	v_pk_mul_f32 v[86:87], v[86:87], v[204:205]
	v_cvt_pk_bf16_f32 v152, v88, v89
	v_cvt_pk_bf16_f32 v153, v90, v91
	v_cvt_pk_bf16_f32 v154, v84, v85
	v_cvt_pk_bf16_f32 v155, v86, v87
	global_store_dwordx4 v[214:215], v[152:155], off offset:256
	v_lshl_add_u64 v[180:181], v[214:215], 0, s[20:21]
	s_waitcnt vmcnt(15)
	v_lshlrev_b32_e32 v184, 16, v156
	v_and_b32_e32 v185, 0xffff0000, v156
	v_lshlrev_b32_e32 v186, 16, v157
	v_and_b32_e32 v187, 0xffff0000, v157
	v_lshlrev_b32_e32 v200, 16, v158
	v_and_b32_e32 v201, 0xffff0000, v158
	v_lshlrev_b32_e32 v204, 16, v159
	v_and_b32_e32 v205, 0xffff0000, v159
	v_max_f32_e32 v184, v184, v184
	v_max_f32_e32 v185, v185, v185
	v_max_f32_e32 v186, v186, v186
	v_max_f32_e32 v187, v187, v187
	v_max_f32_e32 v200, v200, v200
	v_max_f32_e32 v201, v201, v201
	v_max_f32_e32 v204, v204, v204
	v_max_f32_e32 v205, v205, v205
	v_max_f32_e32 v184, 0xda24260, v184
	v_max_f32_e32 v185, 0xda24260, v185
	v_max_f32_e32 v186, 0xda24260, v186
	v_max_f32_e32 v187, 0xda24260, v187
	v_max_f32_e32 v200, 0xda24260, v200
	v_max_f32_e32 v201, 0xda24260, v201
	v_max_f32_e32 v204, 0xda24260, v204
	v_max_f32_e32 v205, 0xda24260, v205
	v_pk_mul_f32 v[80:81], v[80:81], v[184:185]
	v_pk_mul_f32 v[82:83], v[82:83], v[186:187]
	v_pk_mul_f32 v[76:77], v[76:77], v[200:201]
	v_pk_mul_f32 v[78:79], v[78:79], v[204:205]
	v_cvt_pk_bf16_f32 v156, v80, v81
	v_cvt_pk_bf16_f32 v157, v82, v83
	v_cvt_pk_bf16_f32 v158, v76, v77
	v_cvt_pk_bf16_f32 v159, v78, v79
	global_store_dwordx4 v[180:181], v[156:159], off
	s_waitcnt vmcnt(15)
; __device__ __forceinline__ unsigned cvt_pk_bf16(float lo, float hi) { unsigned r; asm volatile("v_cvt_pk_bf16_f32 %0, %1, %2" : "=v"(r) : "v"(lo), "v"(hi)); return r; }
;     __device__ __forceinline__ void operator()(const f32x4 (&acc)[2][2][4][2], const Unit& u, int wr, int wc, int fr, int fq) const {
;     ...
;             for (int bj = 0; bj < 2; ++bj) { f32x4 b0, b1; unpack_bf16x8(gb[cb][bj], b0, b1);
; #pragma unroll
;                 for (int j = 0; j < 4; ++j) { b0[j] = fmaxf(b0[j], 1e-30f); b1[j] = fmaxf(b1[j], 1e-30f); }
;                 const f32x4 v0 = acc[ai][bj][m][0] * b0, v1 = acc[ai][bj][m][1] * b1;
;                 u32x4 w; w.x = cvt_pk_bf16(v0[0], v0[1]); w.y = cvt_pk_bf16(v0[2], v0[3]); w.z = cvt_pk_bf16(v1[0], v1[1]); w.w = cvt_pk_bf16(v1[2], v1[3]);
;                 *(u32x4*)(O + row * 2048 + col0 + bj * HALF) = w; }
;             asm volatile("" ::: "memory"); }
	v_lshlrev_b32_e32 v184, 16, v160
	v_and_b32_e32 v185, 0xffff0000, v160
	v_lshlrev_b32_e32 v186, 16, v161
	v_and_b32_e32 v187, 0xffff0000, v161
	v_lshlrev_b32_e32 v200, 16, v162
	v_and_b32_e32 v201, 0xffff0000, v162
	v_lshlrev_b32_e32 v204, 16, v163
	v_and_b32_e32 v205, 0xffff0000, v163
	v_max_f32_e32 v184, v184, v184
	v_max_f32_e32 v185, v185, v185
	v_max_f32_e32 v186, v186, v186
	v_max_f32_e32 v187, v187, v187
	v_max_f32_e32 v200, v200, v200
	v_max_f32_e32 v201, v201, v201
	v_max_f32_e32 v204, v204, v204
	v_max_f32_e32 v205, v205, v205
	v_max_f32_e32 v184, 0xda24260, v184
	v_max_f32_e32 v185, 0xda24260, v185
	v_max_f32_e32 v186, 0xda24260, v186
	v_max_f32_e32 v187, 0xda24260, v187
	v_max_f32_e32 v200, 0xda24260, v200
	v_max_f32_e32 v201, 0xda24260, v201
	v_max_f32_e32 v204, 0xda24260, v204
	v_max_f32_e32 v205, 0xda24260, v205
	v_pk_mul_f32 v[72:73], v[72:73], v[184:185]
	v_pk_mul_f32 v[74:75], v[74:75], v[186:187]
	v_pk_mul_f32 v[68:69], v[68:69], v[200:201]
	v_pk_mul_f32 v[70:71], v[70:71], v[204:205]
	v_cvt_pk_bf16_f32 v160, v72, v73
	v_cvt_pk_bf16_f32 v161, v74, v75
	v_cvt_pk_bf16_f32 v162, v68, v69
	v_cvt_pk_bf16_f32 v163, v70, v71
	global_store_dwordx4 v[180:181], v[160:163], off offset:256
	v_lshl_add_u64 v[214:215], v[180:181], 0, s[98:99]
	s_waitcnt vmcnt(15)
	v_lshlrev_b32_e32 v184, 16, v196
	v_and_b32_e32 v185, 0xffff0000, v196
	v_lshlrev_b32_e32 v186, 16, v197
	v_and_b32_e32 v187, 0xffff0000, v197
	v_lshlrev_b32_e32 v200, 16, v198
	v_and_b32_e32 v201, 0xffff0000, v198
	v_lshlrev_b32_e32 v204, 16, v199
	v_and_b32_e32 v205, 0xffff0000, v199
	v_max_f32_e32 v184, v184, v184
	v_max_f32_e32 v185, v185, v185
	v_max_f32_e32 v186, v186, v186
	v_max_f32_e32 v187, v187, v187
	v_max_f32_e32 v200, v200, v200
	v_max_f32_e32 v201, v201, v201
	v_max_f32_e32 v204, v204, v204
	v_max_f32_e32 v205, v205, v205
	v_max_f32_e32 v184, 0xda24260, v184
	v_max_f32_e32 v185, 0xda24260, v185
	v_max_f32_e32 v186, 0xda24260, v186
	v_max_f32_e32 v187, 0xda24260, v187
	v_max_f32_e32 v200, 0xda24260, v200
	v_max_f32_e32 v201, 0xda24260, v201
	v_max_f32_e32 v204, 0xda24260, v204
	v_max_f32_e32 v205, 0xda24260, v205
	v_pk_mul_f32 v[64:65], v[64:65], v[184:185]
	v_pk_mul_f32 v[66:67], v[66:67], v[186:187]
	v_pk_mul_f32 v[60:61], v[60:61], v[200:201]
	v_pk_mul_f32 v[62:63], v[62:63], v[204:205]
	v_cvt_pk_bf16_f32 v196, v64, v65
	v_cvt_pk_bf16_f32 v197, v66, v67
	v_cvt_pk_bf16_f32 v198, v60, v61
	v_cvt_pk_bf16_f32 v199, v62, v63
	global_store_dwordx4 v[214:215], v[196:199], off
	s_waitcnt vmcnt(15)
	v_lshlrev_b32_e32 v184, 16, v210
	v_and_b32_e32 v185, 0xffff0000, v210
	v_lshlrev_b32_e32 v186, 16, v211
	v_and_b32_e32 v187, 0xffff0000, v211
	v_lshlrev_b32_e32 v200, 16, v212
	v_and_b32_e32 v201, 0xffff0000, v212
	v_lshlrev_b32_e32 v204, 16, v213
	v_and_b32_e32 v205, 0xffff0000, v213
	v_max_f32_e32 v184, v184, v184
	v_max_f32_e32 v185, v185, v185
	v_max_f32_e32 v186, v186, v186
	v_max_f32_e32 v187, v187, v187
	v_max_f32_e32 v200, v200, v200
	v_max_f32_e32 v201, v201, v201
	v_max_f32_e32 v204, v204, v204
	v_max_f32_e32 v205, v205, v205
	v_max_f32_e32 v184, 0xda24260, v184
	v_max_f32_e32 v185, 0xda24260, v185
	v_max_f32_e32 v186, 0xda24260, v186
	v_max_f32_e32 v187, 0xda24260, v187
	v_max_f32_e32 v200, 0xda24260, v200
	v_max_f32_e32 v201, 0xda24260, v201
	v_max_f32_e32 v204, 0xda24260, v204
	v_max_f32_e32 v205, 0xda24260, v205
	v_pk_mul_f32 v[56:57], v[56:57], v[184:185]
	v_pk_mul_f32 v[58:59], v[58:59], v[186:187]
	v_pk_mul_f32 v[52:53], v[52:53], v[200:201]
	v_pk_mul_f32 v[54:55], v[54:55], v[204:205]
	v_cvt_pk_bf16_f32 v210, v56, v57
	v_cvt_pk_bf16_f32 v211, v58, v59
	v_cvt_pk_bf16_f32 v212, v52, v53
	v_cvt_pk_bf16_f32 v213, v54, v55
	global_store_dwordx4 v[214:215], v[210:213], off offset:256
	v_lshl_add_u64 v[180:181], v[214:215], 0, s[20:21]
	s_waitcnt vmcnt(15)
	v_lshlrev_b32_e32 v184, 16, v224
	v_and_b32_e32 v185, 0xffff0000, v224
	v_lshlrev_b32_e32 v186, 16, v225
	v_and_b32_e32 v187, 0xffff0000, v225
	v_lshlrev_b32_e32 v200, 16, v226
	v_and_b32_e32 v201, 0xffff0000, v226
	v_lshlrev_b32_e32 v204, 16, v227
	v_and_b32_e32 v205, 0xffff0000, v227
	v_max_f32_e32 v184, v184, v184
	v_max_f32_e32 v185, v185, v185
	v_max_f32_e32 v186, v186, v186
	v_max_f32_e32 v187, v187, v187
	v_max_f32_e32 v200, v200, v200
	v_max_f32_e32 v201, v201, v201
	v_max_f32_e32 v204, v204, v204
	v_max_f32_e32 v205, v205, v205
	v_max_f32_e32 v184, 0xda24260, v184
	v_max_f32_e32 v185, 0xda24260, v185
	v_max_f32_e32 v186, 0xda24260, v186
	v_max_f32_e32 v187, 0xda24260, v187
	v_max_f32_e32 v200, 0xda24260, v200
	v_max_f32_e32 v201, 0xda24260, v201
	v_max_f32_e32 v204, 0xda24260, v204
	v_max_f32_e32 v205, 0xda24260, v205
	v_pk_mul_f32 v[48:49], v[48:49], v[184:185]
	v_pk_mul_f32 v[50:51], v[50:51], v[186:187]
	v_pk_mul_f32 v[44:45], v[44:45], v[200:201]
	v_pk_mul_f32 v[46:47], v[46:47], v[204:205]
	v_cvt_pk_bf16_f32 v224, v48, v49
	v_cvt_pk_bf16_f32 v225, v50, v51
	v_cvt_pk_bf16_f32 v226, v44, v45
	v_cvt_pk_bf16_f32 v227, v46, v47
	global_store_dwordx4 v[180:181], v[224:227], off
	s_waitcnt vmcnt(15)
; __device__ __forceinline__ unsigned cvt_pk_bf16(float lo, float hi) { unsigned r; asm volatile("v_cvt_pk_bf16_f32 %0, %1, %2" : "=v"(r) : "v"(lo), "v"(hi)); return r; }
;     __device__ __forceinline__ void operator()(const f32x4 (&acc)[2][2][4][2], const Unit& u, int wr, int wc, int fr, int fq) const {
;     ...
;             for (int bj = 0; bj < 2; ++bj) { f32x4 b0, b1; unpack_bf16x8(gb[cb][bj], b0, b1);
; #pragma unroll
;                 for (int j = 0; j < 4; ++j) { b0[j] = fmaxf(b0[j], 1e-30f); b1[j] = fmaxf(b1[j], 1e-30f); }
;                 const f32x4 v0 = acc[ai][bj][m][0] * b0, v1 = acc[ai][bj][m][1] * b1;
;                 u32x4 w; w.x = cvt_pk_bf16(v0[0], v0[1]); w.y = cvt_pk_bf16(v0[2], v0[3]); w.z = cvt_pk_bf16(v1[0], v1[1]); w.w = cvt_pk_bf16(v1[2], v1[3]);
;                 *(u32x4*)(O + row * 2048 + col0 + bj * HALF) = w; }
;             asm volatile("" ::: "memory"); }
	v_lshlrev_b32_e32 v184, 16, v228
	v_and_b32_e32 v185, 0xffff0000, v228
	v_lshlrev_b32_e32 v186, 16, v229
	v_and_b32_e32 v187, 0xffff0000, v229
	v_lshlrev_b32_e32 v200, 16, v230
	v_and_b32_e32 v201, 0xffff0000, v230
	v_lshlrev_b32_e32 v204, 16, v231
	v_and_b32_e32 v205, 0xffff0000, v231
	v_max_f32_e32 v184, v184, v184
	v_max_f32_e32 v185, v185, v185
	v_max_f32_e32 v186, v186, v186
	v_max_f32_e32 v187, v187, v187
	v_max_f32_e32 v200, v200, v200
	v_max_f32_e32 v201, v201, v201
	v_max_f32_e32 v204, v204, v204
	v_max_f32_e32 v205, v205, v205
	v_max_f32_e32 v184, 0xda24260, v184
	v_max_f32_e32 v185, 0xda24260, v185
	v_max_f32_e32 v186, 0xda24260, v186
	v_max_f32_e32 v187, 0xda24260, v187
	v_max_f32_e32 v200, 0xda24260, v200
	v_max_f32_e32 v201, 0xda24260, v201
	v_max_f32_e32 v204, 0xda24260, v204
	v_max_f32_e32 v205, 0xda24260, v205
	v_pk_mul_f32 v[40:41], v[40:41], v[184:185]
	v_pk_mul_f32 v[42:43], v[42:43], v[186:187]
	v_pk_mul_f32 v[36:37], v[36:37], v[200:201]
	v_pk_mul_f32 v[38:39], v[38:39], v[204:205]
	v_cvt_pk_bf16_f32 v228, v40, v41
	v_cvt_pk_bf16_f32 v229, v42, v43
	v_cvt_pk_bf16_f32 v230, v36, v37
	v_cvt_pk_bf16_f32 v231, v38, v39
	global_store_dwordx4 v[180:181], v[228:231], off offset:256
	v_lshl_add_u64 v[214:215], v[180:181], 0, s[20:21]
	s_waitcnt vmcnt(15)
	v_lshlrev_b32_e32 v184, 16, v232
	v_and_b32_e32 v185, 0xffff0000, v232
	v_lshlrev_b32_e32 v186, 16, v233
	v_and_b32_e32 v187, 0xffff0000, v233
	v_lshlrev_b32_e32 v200, 16, v234
	v_and_b32_e32 v201, 0xffff0000, v234
	v_lshlrev_b32_e32 v204, 16, v235
	v_and_b32_e32 v205, 0xffff0000, v235
	v_max_f32_e32 v184, v184, v184
	v_max_f32_e32 v185, v185, v185
	v_max_f32_e32 v186, v186, v186
	v_max_f32_e32 v187, v187, v187
	v_max_f32_e32 v200, v200, v200
	v_max_f32_e32 v201, v201, v201
	v_max_f32_e32 v204, v204, v204
	v_max_f32_e32 v205, v205, v205
	v_max_f32_e32 v184, 0xda24260, v184
	v_max_f32_e32 v185, 0xda24260, v185
	v_max_f32_e32 v186, 0xda24260, v186
	v_max_f32_e32 v187, 0xda24260, v187
	v_max_f32_e32 v200, 0xda24260, v200
	v_max_f32_e32 v201, 0xda24260, v201
	v_max_f32_e32 v204, 0xda24260, v204
	v_max_f32_e32 v205, 0xda24260, v205
	v_pk_mul_f32 v[32:33], v[32:33], v[184:185]
	v_pk_mul_f32 v[34:35], v[34:35], v[186:187]
	v_pk_mul_f32 v[28:29], v[28:29], v[200:201]
	v_pk_mul_f32 v[30:31], v[30:31], v[204:205]
	v_cvt_pk_bf16_f32 v232, v32, v33
	v_cvt_pk_bf16_f32 v233, v34, v35
	v_cvt_pk_bf16_f32 v234, v28, v29
	v_cvt_pk_bf16_f32 v235, v30, v31
	global_store_dwordx4 v[214:215], v[232:235], off
	s_waitcnt vmcnt(15)
	v_lshlrev_b32_e32 v184, 16, v236
	v_and_b32_e32 v185, 0xffff0000, v236
	v_lshlrev_b32_e32 v186, 16, v237
	v_and_b32_e32 v187, 0xffff0000, v237
	v_lshlrev_b32_e32 v200, 16, v238
	v_and_b32_e32 v201, 0xffff0000, v238
	v_lshlrev_b32_e32 v204, 16, v239
	v_and_b32_e32 v205, 0xffff0000, v239
	v_max_f32_e32 v184, v184, v184
	v_max_f32_e32 v185, v185, v185
	v_max_f32_e32 v186, v186, v186
	v_max_f32_e32 v187, v187, v187
	v_max_f32_e32 v200, v200, v200
	v_max_f32_e32 v201, v201, v201
	v_max_f32_e32 v204, v204, v204
	v_max_f32_e32 v205, v205, v205
	v_max_f32_e32 v184, 0xda24260, v184
	v_max_f32_e32 v185, 0xda24260, v185
	v_max_f32_e32 v186, 0xda24260, v186
	v_max_f32_e32 v187, 0xda24260, v187
	v_max_f32_e32 v200, 0xda24260, v200
	v_max_f32_e32 v201, 0xda24260, v201
	v_max_f32_e32 v204, 0xda24260, v204
	v_max_f32_e32 v205, 0xda24260, v205
	v_pk_mul_f32 v[24:25], v[24:25], v[184:185]
	v_pk_mul_f32 v[26:27], v[26:27], v[186:187]
	v_pk_mul_f32 v[20:21], v[20:21], v[200:201]
	v_pk_mul_f32 v[22:23], v[22:23], v[204:205]
	v_cvt_pk_bf16_f32 v236, v24, v25
	v_cvt_pk_bf16_f32 v237, v26, v27
	v_cvt_pk_bf16_f32 v238, v20, v21
	v_cvt_pk_bf16_f32 v239, v22, v23
	global_store_dwordx4 v[214:215], v[236:239], off offset:256
	v_lshl_add_u64 v[180:181], v[214:215], 0, s[20:21]
	s_waitcnt vmcnt(15)
	v_lshlrev_b32_e32 v184, 16, v240
	v_and_b32_e32 v185, 0xffff0000, v240
	v_lshlrev_b32_e32 v186, 16, v241
	v_and_b32_e32 v187, 0xffff0000, v241
	v_lshlrev_b32_e32 v200, 16, v242
	v_and_b32_e32 v201, 0xffff0000, v242
	v_lshlrev_b32_e32 v204, 16, v243
	v_and_b32_e32 v205, 0xffff0000, v243
	v_max_f32_e32 v184, v184, v184
	v_max_f32_e32 v185, v185, v185
	v_max_f32_e32 v186, v186, v186
	v_max_f32_e32 v187, v187, v187
	v_max_f32_e32 v200, v200, v200
	v_max_f32_e32 v201, v201, v201
	v_max_f32_e32 v204, v204, v204
	v_max_f32_e32 v205, v205, v205
	v_max_f32_e32 v184, 0xda24260, v184
	v_max_f32_e32 v185, 0xda24260, v185
	v_max_f32_e32 v186, 0xda24260, v186
	v_max_f32_e32 v187, 0xda24260, v187
	v_max_f32_e32 v200, 0xda24260, v200
	v_max_f32_e32 v201, 0xda24260, v201
	v_max_f32_e32 v204, 0xda24260, v204
	v_max_f32_e32 v205, 0xda24260, v205
	v_pk_mul_f32 v[16:17], v[16:17], v[184:185]
	v_pk_mul_f32 v[18:19], v[18:19], v[186:187]
	v_pk_mul_f32 v[12:13], v[12:13], v[200:201]
	v_pk_mul_f32 v[14:15], v[14:15], v[204:205]
	v_cvt_pk_bf16_f32 v240, v16, v17
	v_cvt_pk_bf16_f32 v241, v18, v19
	v_cvt_pk_bf16_f32 v242, v12, v13
	v_cvt_pk_bf16_f32 v243, v14, v15
	global_store_dwordx4 v[180:181], v[240:243], off
	s_waitcnt vmcnt(15)
	v_lshlrev_b32_e32 v184, 16, v244
	v_and_b32_e32 v185, 0xffff0000, v244
	v_lshlrev_b32_e32 v186, 16, v245
	v_and_b32_e32 v187, 0xffff0000, v245
	v_lshlrev_b32_e32 v200, 16, v246
	v_and_b32_e32 v201, 0xffff0000, v246
	v_lshlrev_b32_e32 v204, 16, v247
	v_and_b32_e32 v205, 0xffff0000, v247
	v_max_f32_e32 v184, v184, v184
	v_max_f32_e32 v185, v185, v185
	v_max_f32_e32 v186, v186, v186
	v_max_f32_e32 v187, v187, v187
	v_max_f32_e32 v200, v200, v200
	v_max_f32_e32 v201, v201, v201
	v_max_f32_e32 v204, v204, v204
	v_max_f32_e32 v205, v205, v205
	v_max_f32_e32 v184, 0xda24260, v184
	v_max_f32_e32 v185, 0xda24260, v185
	v_max_f32_e32 v186, 0xda24260, v186
	v_max_f32_e32 v187, 0xda24260, v187
	v_max_f32_e32 v200, 0xda24260, v200
	v_max_f32_e32 v201, 0xda24260, v201
	v_max_f32_e32 v204, 0xda24260, v204
	v_max_f32_e32 v205, 0xda24260, v205
	v_pk_mul_f32 v[8:9], v[8:9], v[184:185]
	v_pk_mul_f32 v[10:11], v[10:11], v[186:187]
	v_pk_mul_f32 v[4:5], v[4:5], v[200:201]
	v_pk_mul_f32 v[6:7], v[6:7], v[204:205]
	v_cvt_pk_bf16_f32 v244, v8, v9
	v_cvt_pk_bf16_f32 v245, v10, v11
	v_cvt_pk_bf16_f32 v246, v4, v5
	v_cvt_pk_bf16_f32 v247, v6, v7
	global_store_dwordx4 v[180:181], v[244:247], off offset:256
	s_cmp_eq_u32 s37, s3
	s_mov_b64 s[20:21], -1
	s_cbranch_scc1 .LBB0_748
